# GEMM epilogues: flat->global stores/atomics, counted vmcnt in out-proj epilogue, batched ssq loads in in-proj epilogue, dropped unit-loop header vmcnt(0) drains
# speedup vs baseline: 1.0041x; 1.0041x over previous
; template <class Epi, class Sched, bool ALIGN_EPI = false, bool SP2 = false>
; __device__ __forceinline__ void gemm_phase(PG8_LAS unsigned char* lds, const Gemm g, const Sched& S, const Epi& E, const int tid) {
;     ...
;         const bool has_next = S.next(ui + 1, nxt);
;         const char* nA = has_next ? (const char*)g.A + (size_t)nxt.pm * tstep : cA; const char* nB = has_next ? (const char*)g.Bt + (size_t)nxt.pn * tstep : cB;
;         for (int t = 0; t < nt; t += 2) {
;             const bool last = (t == nt - 2);
;             const char* a1 = cA + (size_t)(t + 1) * kstep;
;             const char* a2 = last ? nA : cA + (size_t)(t + 2) * kstep; const char* b2 = last ? nB : cB + (size_t)(t + 2) * kstep;
;             const char* a3 = a2 + kstep; const char* b3 = b2 + kstep;
;     ...
; #pragma unroll
;         for (int a = 0; a < 2; ++a)
; #pragma unroll
;             for (int b = 0; b < 2; ++b)
; #pragma unroll
;                 for (int m = 0; m < 4; ++m)
; #pragma unroll
;                     for (int n = 0; n < 2; ++n) acc[a][b][m][n] = (f32x4){0.f, 0.f, 0.f, 0.f};
;         cur = nxt; cA = nA; cB = nB; ++ui;
.LBB0_120:
	s_ashr_i32 s27, s26, 31
	s_lshl_b64 s[28:29], s[26:27], 20
	s_add_u32 s28, s93, s28
	s_addc_u32 s29, s95, s29
	s_and_b64 s[34:35], s[4:5], exec
	s_cselect_b32 s27, s29, s9
	s_cselect_b32 s49, s28, s8
	s_ashr_i32 s19, s18, 31
	s_lshl_b64 s[34:35], s[18:19], 20
	s_add_u32 s34, s60, s34
	s_addc_u32 s35, s30, s35
	s_and_b64 s[36:37], s[4:5], exec
	s_cselect_b32 s19, s35, s7
	s_cselect_b32 s50, s34, s6
	s_add_u32 s51, s6, 0x100
	s_addc_u32 s54, s7, 0
	s_add_u32 s6, s8, 0x80080
	v_mov_b32_e32 v2, 0
	s_addc_u32 s7, s9, 0
	s_mov_b32 s55, -2
	s_waitcnt lgkmcnt(0)
	v_mov_b32_e32 v3, v2
	v_mov_b32_e32 v4, v2
	v_mov_b32_e32 v5, v2
	v_mov_b32_e32 v6, v2
	v_mov_b32_e32 v7, v2
	v_mov_b32_e32 v8, v2
	v_mov_b32_e32 v9, v2
	v_mov_b32_e32 v18, v2
	v_mov_b32_e32 v19, v2
	v_mov_b32_e32 v20, v2
	v_mov_b32_e32 v21, v2
	v_mov_b32_e32 v22, v2
	v_mov_b32_e32 v23, v2
	v_mov_b32_e32 v24, v2
	v_mov_b32_e32 v25, v2
	v_mov_b32_e32 v34, v2
	v_mov_b32_e32 v35, v2
	v_mov_b32_e32 v36, v2
	v_mov_b32_e32 v37, v2
	v_mov_b32_e32 v38, v2
	v_mov_b32_e32 v39, v2
	v_mov_b32_e32 v40, v2
	v_mov_b32_e32 v41, v2
	v_mov_b32_e32 v50, v2
	v_mov_b32_e32 v51, v2
	v_mov_b32_e32 v52, v2
	v_mov_b32_e32 v53, v2
	v_mov_b32_e32 v54, v2
	v_mov_b32_e32 v55, v2
	v_mov_b32_e32 v56, v2
	v_mov_b32_e32 v57, v2
	v_mov_b32_e32 v10, v2
	v_mov_b32_e32 v11, v2
	v_mov_b32_e32 v12, v2
	v_mov_b32_e32 v13, v2
	v_mov_b32_e32 v14, v2
	v_mov_b32_e32 v15, v2
	v_mov_b32_e32 v16, v2
	v_mov_b32_e32 v17, v2
	v_mov_b32_e32 v26, v2
	v_mov_b32_e32 v27, v2
	v_mov_b32_e32 v28, v2
	v_mov_b32_e32 v29, v2
	v_mov_b32_e32 v30, v2
	v_mov_b32_e32 v31, v2
	v_mov_b32_e32 v32, v2
	v_mov_b32_e32 v33, v2
	v_mov_b32_e32 v42, v2
	v_mov_b32_e32 v43, v2
	v_mov_b32_e32 v44, v2
	v_mov_b32_e32 v45, v2
	v_mov_b32_e32 v46, v2
	v_mov_b32_e32 v47, v2
	v_mov_b32_e32 v48, v2
	v_mov_b32_e32 v49, v2
	v_mov_b32_e32 v58, v2
	v_mov_b32_e32 v59, v2
	v_mov_b32_e32 v60, v2
	v_mov_b32_e32 v61, v2
	v_mov_b32_e32 v62, v2
	v_mov_b32_e32 v63, v2
	v_mov_b32_e32 v64, v2
	v_mov_b32_e32 v65, v2
	v_mov_b32_e32 v66, v2
	v_mov_b32_e32 v67, v2
	v_mov_b32_e32 v68, v2
	v_mov_b32_e32 v69, v2
	v_mov_b32_e32 v70, v2
	v_mov_b32_e32 v71, v2
	v_mov_b32_e32 v72, v2
	v_mov_b32_e32 v73, v2
	v_mov_b32_e32 v82, v2
	v_mov_b32_e32 v83, v2
	v_mov_b32_e32 v84, v2
	v_mov_b32_e32 v85, v2
	v_mov_b32_e32 v86, v2
	v_mov_b32_e32 v87, v2
	v_mov_b32_e32 v88, v2
	v_mov_b32_e32 v89, v2
	v_mov_b32_e32 v98, v2
	v_mov_b32_e32 v99, v2
	v_mov_b32_e32 v100, v2
	v_mov_b32_e32 v101, v2
	v_mov_b32_e32 v102, v2
	v_mov_b32_e32 v103, v2
	v_mov_b32_e32 v104, v2
	v_mov_b32_e32 v105, v2
	v_mov_b32_e32 v114, v2
	v_mov_b32_e32 v115, v2
	v_mov_b32_e32 v116, v2
	v_mov_b32_e32 v117, v2
	v_mov_b32_e32 v118, v2
	v_mov_b32_e32 v119, v2
	v_mov_b32_e32 v120, v2
	v_mov_b32_e32 v121, v2
	v_mov_b32_e32 v74, v2
	v_mov_b32_e32 v75, v2
	v_mov_b32_e32 v76, v2
	v_mov_b32_e32 v77, v2
	v_mov_b32_e32 v78, v2
	v_mov_b32_e32 v79, v2
	v_mov_b32_e32 v80, v2
	v_mov_b32_e32 v81, v2
	v_mov_b32_e32 v90, v2
	v_mov_b32_e32 v91, v2
	v_mov_b32_e32 v92, v2
	v_mov_b32_e32 v93, v2
	v_mov_b32_e32 v94, v2
	v_mov_b32_e32 v95, v2
	v_mov_b32_e32 v96, v2
	v_mov_b32_e32 v97, v2
	v_mov_b32_e32 v106, v2
	v_mov_b32_e32 v107, v2
	v_mov_b32_e32 v108, v2
	v_mov_b32_e32 v109, v2
	v_mov_b32_e32 v110, v2
	v_mov_b32_e32 v111, v2
	v_mov_b32_e32 v112, v2
	v_mov_b32_e32 v113, v2
	v_mov_b32_e32 v122, v2
	v_mov_b32_e32 v123, v2
	v_mov_b32_e32 v124, v2
	v_mov_b32_e32 v125, v2
	v_mov_b32_e32 v126, v2
	v_mov_b32_e32 v127, v2
	v_mov_b32_e32 v128, v2
	v_mov_b32_e32 v129, v2

; __device__ __forceinline__ unsigned cvt_pk_bf16(float lo, float hi) { unsigned r; asm volatile("v_cvt_pk_bf16_f32 %0, %1, %2" : "=v"(r) : "v"(lo), "v"(hi)); return r; }
; #define EO_LOAD(rr, slot) do { const size_t o_ = (size_t)(row0 + ((rr) >> 2) * 128 + ((rr) & 3) * 16) * DM + col0; _Pragma("unroll") for (int q_ = 0; q_ < 4; ++q_) xr[slot][q_] = *(const f32x4*)(Xin + o_ + (q_ >> 1) * 128 + (q_ & 1) * 16); } while (0)
;     __device__ __forceinline__ void operator()(const f32x4 (&acc)[2][2][4][2], const pg8::Unit& u, int wr, int wc, int fr, int fq) const {
;     ...
;         const int row0 = u.pm * 256 + wr * 64 + fr, col0 = u.pn * 256 + wc * 32 + 4 * fq;
;         f32x4 xr[3][4];
;     ...
;         EO_LOAD(0, 0); EO_LOAD(1, 1);
; #pragma unroll
;         for (int rr = 0; rr < 8; ++rr) { const int ai = rr >> 2, m = rr & 3, row = row0 + ai * 128 + m * 16; const size_t o = (size_t)row * DM + col0; float s = 0.f;
;             if (rr + 2 < 8) EO_LOAD(rr + 2, (rr + 2) % 3);
; #pragma unroll
;             for (int q = 0; q < 4; ++q) { const int bj = q >> 1, n = q & 1; const size_t idx = o + bj * 128 + n * 16; const f32x4 v = xr[rr % 3][q] + acc[ai][bj][m][n]; *(f32x4*)(Out + idx) = v;
;                 if (ssq) { u32x2 w; w.x = cvt_pk_bf16(v[0], v[1]); w.y = cvt_pk_bf16(v[2], v[3]); *(u32x2*)(HBo + idx) = w; s += (v[0] * v[0] + v[1] * v[1]) + (v[2] * v[2] + v[3] * v[3]); } }
;             if (ssq) { s += __shfl_xor(s, 16); s += __shfl_xor(s, 32); if (fq == 0) atomicAdd(ssq + row, s); } }
.LBB0_124:
	s_lshl_b32 s6, s39, 8
	v_mov_b32_e32 v130, v179
	v_mov_b32_e32 v215, v181
	s_add_i32 s6, s6, s44
	v_readlane_b32 s72, v251, 6
	v_add_u32_e32 v190, s6, v130
	s_lshl_b32 s6, s38, 8
	s_or_b32 s6, s6, s45
	v_lshl_add_u32 v192, v215, 2, s6
	v_ashrrev_i32_e32 v191, 31, v190
	v_ashrrev_i32_e32 v193, 31, v192
	v_lshlrev_b64 v[130:131], 13, v[190:191]
	v_lshl_add_u64 v[130:131], s[10:11], 0, v[130:131]
	v_lshlrev_b64 v[132:133], 2, v[192:193]
	v_add_u32_e32 v196, 16, v190
	v_lshl_add_u64 v[130:131], v[130:131], 0, v[132:133]
	v_ashrrev_i32_e32 v197, 31, v196
	global_load_dwordx4 v[198:201], v[130:131], off
	global_load_dwordx4 v[170:173], v[130:131], off offset:64
	global_load_dwordx4 v[166:169], v[130:131], off offset:512
	global_load_dwordx4 v[162:165], v[130:131], off offset:576
	v_lshlrev_b64 v[130:131], 13, v[196:197]
	v_lshl_add_u64 v[130:131], s[10:11], 0, v[130:131]
	v_lshl_add_u64 v[130:131], v[130:131], 0, v[132:133]
	v_add_u32_e32 v194, 32, v190
	global_load_dwordx4 v[158:161], v[130:131], off
	global_load_dwordx4 v[154:157], v[130:131], off offset:64
	global_load_dwordx4 v[150:153], v[130:131], off offset:512
	global_load_dwordx4 v[146:149], v[130:131], off offset:576
	v_lshlrev_b64 v[130:131], 11, v[190:191]
	v_ashrrev_i32_e32 v195, 31, v194
	v_lshl_add_u64 v[218:219], v[130:131], 0, v[192:193]
	v_lshlrev_b64 v[130:131], 13, v[194:195]
	v_lshl_add_u64 v[130:131], s[10:11], 0, v[130:131]
	v_lshl_add_u64 v[130:131], v[130:131], 0, v[132:133]
	global_load_dwordx4 v[142:145], v[130:131], off
	global_load_dwordx4 v[138:141], v[130:131], off offset:64
	global_load_dwordx4 v[134:137], v[130:131], off offset:512
	s_nop 0
	global_load_dwordx4 v[130:133], v[130:131], off offset:576
	v_readlane_b32 s86, v251, 20
	v_readlane_b32 s87, v251, 21
	v_mov_b32_e32 v216, 0
	s_andn2_b64 vcc, exec, s[12:13]
	v_readlane_b32 s73, v251, 7
	v_readlane_b32 s74, v251, 8
	v_readlane_b32 s75, v251, 9
	v_readlane_b32 s76, v251, 10
	v_readlane_b32 s77, v251, 11
	v_readlane_b32 s78, v251, 12
	v_readlane_b32 s79, v251, 13
	v_readlane_b32 s80, v251, 14
	v_readlane_b32 s81, v251, 15
	v_readlane_b32 s82, v251, 16
	v_readlane_b32 s83, v251, 17
	v_readlane_b32 s84, v251, 18
	v_readlane_b32 s85, v251, 19
	s_waitcnt vmcnt(8)
	v_pk_add_f32 v[128:129], v[128:129], v[200:201]
	v_cndmask_b32_e64 v200, 0, 1, s[12:13]
	v_pk_add_f32 v[126:127], v[126:127], v[198:199]
	v_lshl_add_u64 v[198:199], v[218:219], 2, s[86:87]
	v_cmp_ne_u32_e64 s[6:7], 1, v200
	v_lshl_add_u64 v[200:201], v[218:219], 1, s[22:23]
	global_store_dwordx4 v[198:199], v[126:129], off
	s_cbranch_vccnz .LBB0_126
	v_cvt_pk_bf16_f32 v216, v126, v127
	v_cvt_pk_bf16_f32 v217, v128, v129
	s_nop 0
	v_pk_mul_f32 v[128:129], v[128:129], v[128:129]
	v_pk_mul_f32 v[126:127], v[126:127], v[126:127]
	global_store_dwordx2 v[200:201], v[216:217], off
	v_pk_mov_b32 v[216:217], v[126:127], v[128:129] op_sel:[1,0]
	v_mov_b32_e32 v127, v129
	v_pk_add_f32 v[126:127], v[216:217], v[126:127]
	s_nop 0
	v_add_f32_e32 v216, v126, v127
.LBB0_126:
	v_pk_add_f32 v[124:125], v[124:125], v[172:173]
	v_pk_add_f32 v[122:123], v[122:123], v[170:171]
	s_and_b64 vcc, exec, s[6:7]
	global_store_dwordx4 v[198:199], v[122:125], off offset:64
	s_cbranch_vccnz .LBB0_128
	v_cvt_pk_bf16_f32 v126, v122, v123
	v_cvt_pk_bf16_f32 v127, v124, v125
	s_nop 0
	v_pk_mul_f32 v[124:125], v[124:125], v[124:125]
	v_pk_mul_f32 v[122:123], v[122:123], v[122:123]
	global_store_dwordx2 v[200:201], v[126:127], off offset:32
	v_pk_mov_b32 v[126:127], v[122:123], v[124:125] op_sel:[1,0]
	v_mov_b32_e32 v123, v125
	v_pk_add_f32 v[122:123], v[126:127], v[122:123]
	s_nop 0
	v_add_f32_e32 v122, v122, v123
	v_add_f32_e32 v216, v122, v216
.LBB0_128:
	v_readlane_b32 s54, v250, 12
	v_pk_add_f32 v[120:121], v[120:121], v[168:169]
	v_pk_add_f32 v[118:119], v[118:119], v[166:167]
	s_and_b64 vcc, exec, s[6:7]
	v_readlane_b32 s55, v250, 13
	global_store_dwordx4 v[198:199], v[118:121], off offset:512
	s_cbranch_vccnz .LBB0_130
	v_cvt_pk_bf16_f32 v122, v118, v119
	v_cvt_pk_bf16_f32 v123, v120, v121
	s_nop 0
	v_pk_mul_f32 v[120:121], v[120:121], v[120:121]
	v_pk_mul_f32 v[118:119], v[118:119], v[118:119]
	global_store_dwordx2 v[200:201], v[122:123], off offset:256
	v_pk_mov_b32 v[122:123], v[118:119], v[120:121] op_sel:[1,0]
	v_mov_b32_e32 v119, v121
	v_pk_add_f32 v[118:119], v[122:123], v[118:119]
	s_nop 0
	v_add_f32_e32 v118, v118, v119
	v_add_f32_e32 v216, v118, v216
.LBB0_130:
	v_pk_add_f32 v[116:117], v[116:117], v[164:165]
	v_pk_add_f32 v[114:115], v[114:115], v[162:163]
	s_and_b64 vcc, exec, s[6:7]
	s_mov_b64 s[36:37], 0
	global_store_dwordx4 v[198:199], v[114:117], off offset:576
	s_cbranch_vccnz .LBB0_132
	v_cvt_pk_bf16_f32 v118, v114, v115
	v_cvt_pk_bf16_f32 v119, v116, v117
	s_nop 0
	v_pk_mul_f32 v[116:117], v[116:117], v[116:117]
	v_pk_mul_f32 v[114:115], v[114:115], v[114:115]
	global_store_dwordx2 v[200:201], v[118:119], off offset:288
	v_pk_mov_b32 v[118:119], v[114:115], v[116:117] op_sel:[1,0]
	v_mov_b32_e32 v115, v117
	v_pk_add_f32 v[114:115], v[118:119], v[114:115]
	s_mov_b64 s[36:37], s[14:15]
	v_add_f32_e32 v114, v114, v115
	v_add_f32_e32 v216, v114, v216
.LBB0_132:
	s_cmp_eq_u64 s[36:37], 0
	v_cmp_eq_u32_e64 s[8:9], 0, v215
	s_cbranch_scc1 .LBB0_136
	v_and_b32_e32 v115, 64, v204
	v_xor_b32_e32 v114, 16, v204
	v_add_u32_e32 v115, 64, v115
	v_cmp_lt_i32_e32 vcc, v114, v115
	v_xor_b32_e32 v116, 32, v204
	s_nop 0
	v_cndmask_b32_e32 v114, v204, v114, vcc
	v_lshlrev_b32_e32 v114, 2, v114
	ds_bpermute_b32 v114, v114, v216
	v_cmp_lt_i32_e32 vcc, v116, v115
	s_waitcnt lgkmcnt(0)
	v_add_f32_e32 v114, v216, v114
	v_cndmask_b32_e32 v115, v204, v116, vcc
	v_lshlrev_b32_e32 v115, 2, v115
	ds_bpermute_b32 v115, v115, v114
	s_and_saveexec_b64 s[38:39], s[8:9]
	s_cbranch_execz .LBB0_135
	v_lshl_add_u64 v[116:117], v[190:191], 2, s[36:37]
	s_waitcnt lgkmcnt(0)
	v_add_f32_e32 v114, v114, v115
	global_atomic_add_f32 v[116:117], v114, off

; __device__ __forceinline__ unsigned cvt_pk_bf16(float lo, float hi) { unsigned r; asm volatile("v_cvt_pk_bf16_f32 %0, %1, %2" : "=v"(r) : "v"(lo), "v"(hi)); return r; }
; #define EO_LOAD(rr, slot) do { const size_t o_ = (size_t)(row0 + ((rr) >> 2) * 128 + ((rr) & 3) * 16) * DM + col0; _Pragma("unroll") for (int q_ = 0; q_ < 4; ++q_) xr[slot][q_] = *(const f32x4*)(Xin + o_ + (q_ >> 1) * 128 + (q_ & 1) * 16); } while (0)
;     __device__ __forceinline__ void operator()(const f32x4 (&acc)[2][2][4][2], const pg8::Unit& u, int wr, int wc, int fr, int fq) const {
;     ...
;         EO_LOAD(0, 0); EO_LOAD(1, 1);
; #pragma unroll
;         for (int rr = 0; rr < 8; ++rr) { const int ai = rr >> 2, m = rr & 3, row = row0 + ai * 128 + m * 16; const size_t o = (size_t)row * DM + col0; float s = 0.f;
;             if (rr + 2 < 8) EO_LOAD(rr + 2, (rr + 2) % 3);
; #pragma unroll
;             for (int q = 0; q < 4; ++q) { const int bj = q >> 1, n = q & 1; const size_t idx = o + bj * 128 + n * 16; const f32x4 v = xr[rr % 3][q] + acc[ai][bj][m][n]; *(f32x4*)(Out + idx) = v;
;                 if (ssq) { u32x2 w; w.x = cvt_pk_bf16(v[0], v[1]); w.y = cvt_pk_bf16(v[2], v[3]); *(u32x2*)(HBo + idx) = w; s += (v[0] * v[0] + v[1] * v[1]) + (v[2] * v[2] + v[3] * v[3]); } }
;             if (ssq) { s += __shfl_xor(s, 16); s += __shfl_xor(s, 32); if (fq == 0) atomicAdd(ssq + row, s); } }
.LBB0_136:
	v_add_u32_e32 v162, 48, v190
	v_ashrrev_i32_e32 v163, 31, v162
	s_waitcnt lgkmcnt(0)
	v_lshlrev_b64 v[114:115], 13, v[162:163]
	v_lshl_add_u64 v[114:115], s[10:11], 0, v[114:115]
	v_lshl_add_u64 v[114:115], v[192:193], 2, v[114:115]
	global_load_dwordx4 v[126:129], v[114:115], off
	global_load_dwordx4 v[122:125], v[114:115], off offset:64
	global_load_dwordx4 v[118:121], v[114:115], off offset:512
	s_nop 0
	global_load_dwordx4 v[114:117], v[114:115], off offset:576
	v_lshlrev_b64 v[164:165], 11, v[196:197]
	v_readlane_b32 s72, v251, 6
	v_lshl_add_u64 v[166:167], v[164:165], 0, v[192:193]
	v_readlane_b32 s86, v251, 20
	v_readlane_b32 s87, v251, 21
	s_cmp_eq_u64 s[12:13], 0
	s_cbranch_scc1 .Lmy_eo_r1_n
	s_waitcnt vmcnt(17)
	s_branch .Lmy_eo_r1_d
.Lmy_eo_r1_n:
	s_waitcnt vmcnt(12)
.Lmy_eo_r1_d:
	v_pk_add_f32 v[112:113], v[112:113], v[160:161]
	v_pk_add_f32 v[110:111], v[110:111], v[158:159]
	v_lshl_add_u64 v[160:161], v[166:167], 2, s[86:87]
	v_mov_b32_e32 v164, 0
	s_and_b64 vcc, exec, s[6:7]
	v_lshl_add_u64 v[158:159], v[166:167], 1, s[22:23]
	v_readlane_b32 s73, v251, 7
	v_readlane_b32 s74, v251, 8
	v_readlane_b32 s75, v251, 9
	v_readlane_b32 s76, v251, 10
	v_readlane_b32 s77, v251, 11
	v_readlane_b32 s78, v251, 12
	v_readlane_b32 s79, v251, 13
	v_readlane_b32 s80, v251, 14
	v_readlane_b32 s81, v251, 15
	v_readlane_b32 s82, v251, 16
	v_readlane_b32 s83, v251, 17
	v_readlane_b32 s84, v251, 18
	v_readlane_b32 s85, v251, 19
	global_store_dwordx4 v[160:161], v[110:113], off
	s_cbranch_vccnz .LBB0_138
	v_cvt_pk_bf16_f32 v164, v110, v111
	v_cvt_pk_bf16_f32 v165, v112, v113
	s_nop 0
	v_pk_mul_f32 v[112:113], v[112:113], v[112:113]
	v_pk_mul_f32 v[110:111], v[110:111], v[110:111]
	global_store_dwordx2 v[158:159], v[164:165], off
	v_pk_mov_b32 v[164:165], v[110:111], v[112:113] op_sel:[1,0]
	v_mov_b32_e32 v111, v113
	v_pk_add_f32 v[110:111], v[164:165], v[110:111]
	s_nop 0
	v_add_f32_e32 v164, v110, v111
.LBB0_138:
	v_pk_add_f32 v[108:109], v[108:109], v[156:157]
	v_pk_add_f32 v[106:107], v[106:107], v[154:155]
	s_and_b64 vcc, exec, s[6:7]
	global_store_dwordx4 v[160:161], v[106:109], off offset:64
	s_cbranch_vccnz .LBB0_140
	v_cvt_pk_bf16_f32 v110, v106, v107
	v_cvt_pk_bf16_f32 v111, v108, v109
	s_nop 0
	v_pk_mul_f32 v[108:109], v[108:109], v[108:109]
	v_pk_mul_f32 v[106:107], v[106:107], v[106:107]
	global_store_dwordx2 v[158:159], v[110:111], off offset:32
	v_pk_mov_b32 v[110:111], v[106:107], v[108:109] op_sel:[1,0]
	v_mov_b32_e32 v107, v109
	v_pk_add_f32 v[106:107], v[110:111], v[106:107]
	s_nop 0
	v_add_f32_e32 v106, v106, v107
	v_add_f32_e32 v164, v106, v164
.LBB0_140:
	v_pk_add_f32 v[104:105], v[104:105], v[152:153]
	v_pk_add_f32 v[102:103], v[102:103], v[150:151]
	s_and_b64 vcc, exec, s[6:7]
	global_store_dwordx4 v[160:161], v[102:105], off offset:512
	s_cbranch_vccnz .LBB0_142
	v_cvt_pk_bf16_f32 v106, v102, v103
	v_cvt_pk_bf16_f32 v107, v104, v105
	s_nop 0
	v_pk_mul_f32 v[104:105], v[104:105], v[104:105]
	v_pk_mul_f32 v[102:103], v[102:103], v[102:103]
	global_store_dwordx2 v[158:159], v[106:107], off offset:256
	v_pk_mov_b32 v[106:107], v[102:103], v[104:105] op_sel:[1,0]
	v_mov_b32_e32 v103, v105
	v_pk_add_f32 v[102:103], v[106:107], v[102:103]
	s_nop 0
	v_add_f32_e32 v102, v102, v103
	v_add_f32_e32 v164, v102, v164
.LBB0_142:
	v_pk_add_f32 v[100:101], v[100:101], v[148:149]
	v_pk_add_f32 v[98:99], v[98:99], v[146:147]
	s_and_b64 vcc, exec, s[6:7]
	s_mov_b64 s[36:37], 0
	global_store_dwordx4 v[160:161], v[98:101], off offset:576
	s_cbranch_vccnz .LBB0_144
	v_cvt_pk_bf16_f32 v102, v98, v99
	v_cvt_pk_bf16_f32 v103, v100, v101
	s_nop 0
	v_pk_mul_f32 v[100:101], v[100:101], v[100:101]
	v_pk_mul_f32 v[98:99], v[98:99], v[98:99]
	global_store_dwordx2 v[158:159], v[102:103], off offset:288
	v_pk_mov_b32 v[102:103], v[98:99], v[100:101] op_sel:[1,0]
	v_mov_b32_e32 v99, v101
	v_pk_add_f32 v[98:99], v[102:103], v[98:99]
	s_mov_b64 s[36:37], s[14:15]
	v_add_f32_e32 v98, v98, v99
	v_add_f32_e32 v164, v98, v164
.LBB0_144:
	s_cmp_eq_u64 s[36:37], 0
	s_cbranch_scc1 .LBB0_148
	v_and_b32_e32 v99, 64, v204
	v_xor_b32_e32 v98, 16, v204
	v_add_u32_e32 v99, 64, v99
	v_cmp_lt_i32_e32 vcc, v98, v99
	v_xor_b32_e32 v100, 32, v204
	s_nop 0
	v_cndmask_b32_e32 v98, v204, v98, vcc
	v_lshlrev_b32_e32 v98, 2, v98
	ds_bpermute_b32 v98, v98, v164
	v_cmp_lt_i32_e32 vcc, v100, v99
	s_waitcnt lgkmcnt(0)
	v_add_f32_e32 v98, v164, v98
	v_cndmask_b32_e32 v99, v204, v100, vcc
	v_lshlrev_b32_e32 v99, 2, v99
	ds_bpermute_b32 v99, v99, v98
	s_and_saveexec_b64 s[38:39], s[8:9]
	s_cbranch_execz .LBB0_147
	v_lshl_add_u64 v[100:101], v[190:191], 2, s[36:37]
	s_waitcnt lgkmcnt(0)
	v_add_f32_e32 v98, v98, v99
	global_atomic_add_f32 v[100:101], v98, off offset:64

; __device__ __forceinline__ unsigned cvt_pk_bf16(float lo, float hi) { unsigned r; asm volatile("v_cvt_pk_bf16_f32 %0, %1, %2" : "=v"(r) : "v"(lo), "v"(hi)); return r; }
; #define EO_LOAD(rr, slot) do { const size_t o_ = (size_t)(row0 + ((rr) >> 2) * 128 + ((rr) & 3) * 16) * DM + col0; _Pragma("unroll") for (int q_ = 0; q_ < 4; ++q_) xr[slot][q_] = *(const f32x4*)(Xin + o_ + (q_ >> 1) * 128 + (q_ & 1) * 16); } while (0)
;     __device__ __forceinline__ void operator()(const f32x4 (&acc)[2][2][4][2], const pg8::Unit& u, int wr, int wc, int fr, int fq) const {
;     ...
;         EO_LOAD(0, 0); EO_LOAD(1, 1);
; #pragma unroll
;         for (int rr = 0; rr < 8; ++rr) { const int ai = rr >> 2, m = rr & 3, row = row0 + ai * 128 + m * 16; const size_t o = (size_t)row * DM + col0; float s = 0.f;
;             if (rr + 2 < 8) EO_LOAD(rr + 2, (rr + 2) % 3);
; #pragma unroll
;             for (int q = 0; q < 4; ++q) { const int bj = q >> 1, n = q & 1; const size_t idx = o + bj * 128 + n * 16; const f32x4 v = xr[rr % 3][q] + acc[ai][bj][m][n]; *(f32x4*)(Out + idx) = v;
;                 if (ssq) { u32x2 w; w.x = cvt_pk_bf16(v[0], v[1]); w.y = cvt_pk_bf16(v[2], v[3]); *(u32x2*)(HBo + idx) = w; s += (v[0] * v[0] + v[1] * v[1]) + (v[2] * v[2] + v[3] * v[3]); } }
;             if (ssq) { s += __shfl_xor(s, 16); s += __shfl_xor(s, 32); if (fq == 0) atomicAdd(ssq + row, s); } }
.LBB0_148:
	v_add_u32_e32 v146, 0x80, v190
	v_ashrrev_i32_e32 v147, 31, v146
	s_waitcnt lgkmcnt(0)
	v_lshlrev_b64 v[98:99], 13, v[146:147]
	v_lshl_add_u64 v[98:99], s[10:11], 0, v[98:99]
	v_lshl_add_u64 v[98:99], v[192:193], 2, v[98:99]
	global_load_dwordx4 v[110:113], v[98:99], off
	global_load_dwordx4 v[106:109], v[98:99], off offset:64
	global_load_dwordx4 v[102:105], v[98:99], off offset:512
	s_nop 0
	global_load_dwordx4 v[98:101], v[98:99], off offset:576
	v_lshlrev_b64 v[148:149], 11, v[194:195]
	v_readlane_b32 s72, v251, 6
	v_lshl_add_u64 v[150:151], v[148:149], 0, v[192:193]
	v_readlane_b32 s86, v251, 20
	v_readlane_b32 s87, v251, 21
	s_cmp_eq_u64 s[12:13], 0
	s_cbranch_scc1 .Lmy_eo_r2_n
	s_waitcnt vmcnt(26)
	s_branch .Lmy_eo_r2_d
.Lmy_eo_r2_n:
	s_waitcnt vmcnt(16)
.Lmy_eo_r2_d:
	v_pk_add_f32 v[96:97], v[96:97], v[144:145]
	v_pk_add_f32 v[94:95], v[94:95], v[142:143]
	v_lshl_add_u64 v[144:145], v[150:151], 2, s[86:87]
	v_mov_b32_e32 v148, 0
	s_and_b64 vcc, exec, s[6:7]
	v_lshl_add_u64 v[142:143], v[150:151], 1, s[22:23]
	v_readlane_b32 s73, v251, 7
	v_readlane_b32 s74, v251, 8
	v_readlane_b32 s75, v251, 9
	v_readlane_b32 s76, v251, 10
	v_readlane_b32 s77, v251, 11
	v_readlane_b32 s78, v251, 12
	v_readlane_b32 s79, v251, 13
	v_readlane_b32 s80, v251, 14
	v_readlane_b32 s81, v251, 15
	v_readlane_b32 s82, v251, 16
	v_readlane_b32 s83, v251, 17
	v_readlane_b32 s84, v251, 18
	v_readlane_b32 s85, v251, 19
	global_store_dwordx4 v[144:145], v[94:97], off
	s_cbranch_vccnz .LBB0_150
	v_cvt_pk_bf16_f32 v148, v94, v95
	v_cvt_pk_bf16_f32 v149, v96, v97
	s_nop 0
	v_pk_mul_f32 v[96:97], v[96:97], v[96:97]
	v_pk_mul_f32 v[94:95], v[94:95], v[94:95]
	global_store_dwordx2 v[142:143], v[148:149], off
	v_pk_mov_b32 v[148:149], v[94:95], v[96:97] op_sel:[1,0]
	v_mov_b32_e32 v95, v97
	v_pk_add_f32 v[94:95], v[148:149], v[94:95]
	s_nop 0
	v_add_f32_e32 v148, v94, v95
.LBB0_150:
	v_pk_add_f32 v[92:93], v[92:93], v[140:141]
	v_pk_add_f32 v[90:91], v[90:91], v[138:139]
	s_and_b64 vcc, exec, s[6:7]
	global_store_dwordx4 v[144:145], v[90:93], off offset:64
	s_cbranch_vccnz .LBB0_152
	v_cvt_pk_bf16_f32 v94, v90, v91
	v_cvt_pk_bf16_f32 v95, v92, v93
	s_nop 0
	v_pk_mul_f32 v[92:93], v[92:93], v[92:93]
	v_pk_mul_f32 v[90:91], v[90:91], v[90:91]
	global_store_dwordx2 v[142:143], v[94:95], off offset:32
	v_pk_mov_b32 v[94:95], v[90:91], v[92:93] op_sel:[1,0]
	v_mov_b32_e32 v91, v93
	v_pk_add_f32 v[90:91], v[94:95], v[90:91]
	s_nop 0
	v_add_f32_e32 v90, v90, v91
	v_add_f32_e32 v148, v90, v148
.LBB0_152:
	v_pk_add_f32 v[88:89], v[88:89], v[136:137]
	v_pk_add_f32 v[86:87], v[86:87], v[134:135]
	s_and_b64 vcc, exec, s[6:7]
	global_store_dwordx4 v[144:145], v[86:89], off offset:512
	s_cbranch_vccnz .LBB0_154
	v_cvt_pk_bf16_f32 v90, v86, v87
	v_cvt_pk_bf16_f32 v91, v88, v89
	s_nop 0
	v_pk_mul_f32 v[88:89], v[88:89], v[88:89]
	v_pk_mul_f32 v[86:87], v[86:87], v[86:87]
	global_store_dwordx2 v[142:143], v[90:91], off offset:256
	v_pk_mov_b32 v[90:91], v[86:87], v[88:89] op_sel:[1,0]
	v_mov_b32_e32 v87, v89
	v_pk_add_f32 v[86:87], v[90:91], v[86:87]
	s_nop 0
	v_add_f32_e32 v86, v86, v87
	v_add_f32_e32 v148, v86, v148
.LBB0_154:
	v_pk_add_f32 v[84:85], v[84:85], v[132:133]
	v_pk_add_f32 v[82:83], v[82:83], v[130:131]
	s_and_b64 vcc, exec, s[6:7]
	s_mov_b64 s[36:37], 0
	global_store_dwordx4 v[144:145], v[82:85], off offset:576
	s_cbranch_vccnz .LBB0_156
	v_cvt_pk_bf16_f32 v86, v82, v83
	v_cvt_pk_bf16_f32 v87, v84, v85
	s_nop 0
	v_pk_mul_f32 v[84:85], v[84:85], v[84:85]
	v_pk_mul_f32 v[82:83], v[82:83], v[82:83]
	global_store_dwordx2 v[142:143], v[86:87], off offset:288
	v_pk_mov_b32 v[86:87], v[82:83], v[84:85] op_sel:[1,0]
	v_mov_b32_e32 v83, v85
	v_pk_add_f32 v[82:83], v[86:87], v[82:83]
	s_mov_b64 s[36:37], s[14:15]
	v_add_f32_e32 v82, v82, v83
	v_add_f32_e32 v148, v82, v148
.LBB0_156:
	s_cmp_eq_u64 s[36:37], 0
	s_cbranch_scc1 .LBB0_160
	v_and_b32_e32 v83, 64, v204
	v_xor_b32_e32 v82, 16, v204
	v_add_u32_e32 v83, 64, v83
	v_cmp_lt_i32_e32 vcc, v82, v83
	v_xor_b32_e32 v84, 32, v204
	s_nop 0
	v_cndmask_b32_e32 v82, v204, v82, vcc
	v_lshlrev_b32_e32 v82, 2, v82
	ds_bpermute_b32 v82, v82, v148
	v_cmp_lt_i32_e32 vcc, v84, v83
	s_waitcnt lgkmcnt(0)
	v_add_f32_e32 v82, v148, v82
	v_cndmask_b32_e32 v83, v204, v84, vcc
	v_lshlrev_b32_e32 v83, 2, v83
	ds_bpermute_b32 v83, v83, v82
	s_and_saveexec_b64 s[38:39], s[8:9]
	s_cbranch_execz .LBB0_159
	v_lshl_add_u64 v[84:85], v[190:191], 2, s[36:37]
	s_waitcnt lgkmcnt(0)
	v_add_f32_e32 v82, v82, v83
	global_atomic_add_f32 v[84:85], v82, off offset:128

; #define EO_LOAD(rr, slot) do { const size_t o_ = (size_t)(row0 + ((rr) >> 2) * 128 + ((rr) & 3) * 16) * DM + col0; _Pragma("unroll") for (int q_ = 0; q_ < 4; ++q_) xr[slot][q_] = *(const f32x4*)(Xin + o_ + (q_ >> 1) * 128 + (q_ & 1) * 16); } while (0)
;     __device__ __forceinline__ void operator()(const f32x4 (&acc)[2][2][4][2], const pg8::Unit& u, int wr, int wc, int fr, int fq) const {
;     ...
;         EO_LOAD(0, 0); EO_LOAD(1, 1);
; #pragma unroll
;         for (int rr = 0; rr < 8; ++rr) { const int ai = rr >> 2, m = rr & 3, row = row0 + ai * 128 + m * 16; const size_t o = (size_t)row * DM + col0; float s = 0.f;
;             if (rr + 2 < 8) EO_LOAD(rr + 2, (rr + 2) % 3);
.LBB0_160:
	v_add_u32_e32 v130, 0x90, v190
	v_ashrrev_i32_e32 v131, 31, v130
	s_waitcnt lgkmcnt(0)
	v_lshlrev_b64 v[82:83], 13, v[130:131]
	v_lshl_add_u64 v[82:83], s[10:11], 0, v[82:83]
	v_lshl_add_u64 v[82:83], v[192:193], 2, v[82:83]
	global_load_dwordx4 v[94:97], v[82:83], off
	global_load_dwordx4 v[90:93], v[82:83], off offset:64
	global_load_dwordx4 v[86:89], v[82:83], off offset:512
	s_nop 0
	global_load_dwordx4 v[82:85], v[82:83], off offset:576
	v_lshlrev_b64 v[132:133], 11, v[162:163]
	v_readlane_b32 s72, v251, 6
	v_lshl_add_u64 v[134:135], v[132:133], 0, v[192:193]
	v_readlane_b32 s86, v251, 20
	v_readlane_b32 s87, v251, 21
	s_cmp_eq_u64 s[12:13], 0
	s_cbranch_scc1 .Lmy_eo_r3_n
	s_waitcnt vmcnt(26)
	s_branch .Lmy_eo_r3_d

; __device__ __forceinline__ unsigned cvt_pk_bf16(float lo, float hi) { unsigned r; asm volatile("v_cvt_pk_bf16_f32 %0, %1, %2" : "=v"(r) : "v"(lo), "v"(hi)); return r; }
; #define EO_LOAD(rr, slot) do { const size_t o_ = (size_t)(row0 + ((rr) >> 2) * 128 + ((rr) & 3) * 16) * DM + col0; _Pragma("unroll") for (int q_ = 0; q_ < 4; ++q_) xr[slot][q_] = *(const f32x4*)(Xin + o_ + (q_ >> 1) * 128 + (q_ & 1) * 16); } while (0)
;     __device__ __forceinline__ void operator()(const f32x4 (&acc)[2][2][4][2], const pg8::Unit& u, int wr, int wc, int fr, int fq) const {
;     ...
;         for (int rr = 0; rr < 8; ++rr) { const int ai = rr >> 2, m = rr & 3, row = row0 + ai * 128 + m * 16; const size_t o = (size_t)row * DM + col0; float s = 0.f;
;             if (rr + 2 < 8) EO_LOAD(rr + 2, (rr + 2) % 3);
; #pragma unroll
;             for (int q = 0; q < 4; ++q) { const int bj = q >> 1, n = q & 1; const size_t idx = o + bj * 128 + n * 16; const f32x4 v = xr[rr % 3][q] + acc[ai][bj][m][n]; *(f32x4*)(Out + idx) = v;
;                 if (ssq) { u32x2 w; w.x = cvt_pk_bf16(v[0], v[1]); w.y = cvt_pk_bf16(v[2], v[3]); *(u32x2*)(HBo + idx) = w; s += (v[0] * v[0] + v[1] * v[1]) + (v[2] * v[2] + v[3] * v[3]); } }
;             if (ssq) { s += __shfl_xor(s, 16); s += __shfl_xor(s, 32); if (fq == 0) atomicAdd(ssq + row, s); } }
.Lmy_eo_r3_d:
	v_pk_add_f32 v[80:81], v[80:81], v[128:129]
	v_pk_add_f32 v[78:79], v[78:79], v[126:127]
	v_lshl_add_u64 v[128:129], v[134:135], 2, s[86:87]
	v_mov_b32_e32 v132, 0
	s_and_b64 vcc, exec, s[6:7]
	v_lshl_add_u64 v[126:127], v[134:135], 1, s[22:23]
	v_readlane_b32 s73, v251, 7
	v_readlane_b32 s74, v251, 8
	v_readlane_b32 s75, v251, 9
	v_readlane_b32 s76, v251, 10
	v_readlane_b32 s77, v251, 11
	v_readlane_b32 s78, v251, 12
	v_readlane_b32 s79, v251, 13
	v_readlane_b32 s80, v251, 14
	v_readlane_b32 s81, v251, 15
	v_readlane_b32 s82, v251, 16
	v_readlane_b32 s83, v251, 17
	v_readlane_b32 s84, v251, 18
	v_readlane_b32 s85, v251, 19
	global_store_dwordx4 v[128:129], v[78:81], off
	s_cbranch_vccnz .LBB0_162
	v_cvt_pk_bf16_f32 v132, v78, v79
	v_cvt_pk_bf16_f32 v133, v80, v81
	s_nop 0
	v_pk_mul_f32 v[80:81], v[80:81], v[80:81]
	v_pk_mul_f32 v[78:79], v[78:79], v[78:79]
	global_store_dwordx2 v[126:127], v[132:133], off
	v_pk_mov_b32 v[132:133], v[78:79], v[80:81] op_sel:[1,0]
	v_mov_b32_e32 v79, v81
	v_pk_add_f32 v[78:79], v[132:133], v[78:79]
	s_nop 0
	v_add_f32_e32 v132, v78, v79
.LBB0_162:
	v_pk_add_f32 v[76:77], v[76:77], v[124:125]
	v_pk_add_f32 v[74:75], v[74:75], v[122:123]
	s_and_b64 vcc, exec, s[6:7]
	global_store_dwordx4 v[128:129], v[74:77], off offset:64
	s_cbranch_vccnz .LBB0_164
	v_cvt_pk_bf16_f32 v78, v74, v75
	v_cvt_pk_bf16_f32 v79, v76, v77
	s_nop 0
	v_pk_mul_f32 v[76:77], v[76:77], v[76:77]
	v_pk_mul_f32 v[74:75], v[74:75], v[74:75]
	global_store_dwordx2 v[126:127], v[78:79], off offset:32
	v_pk_mov_b32 v[78:79], v[74:75], v[76:77] op_sel:[1,0]
	v_mov_b32_e32 v75, v77
	v_pk_add_f32 v[74:75], v[78:79], v[74:75]
	s_nop 0
	v_add_f32_e32 v74, v74, v75
	v_add_f32_e32 v132, v74, v132
.LBB0_164:
	v_pk_add_f32 v[72:73], v[72:73], v[120:121]
	v_pk_add_f32 v[70:71], v[70:71], v[118:119]
	s_and_b64 vcc, exec, s[6:7]
	global_store_dwordx4 v[128:129], v[70:73], off offset:512
	s_cbranch_vccnz .LBB0_166
	v_cvt_pk_bf16_f32 v74, v70, v71
	v_cvt_pk_bf16_f32 v75, v72, v73
	s_nop 0
	v_pk_mul_f32 v[72:73], v[72:73], v[72:73]
	v_pk_mul_f32 v[70:71], v[70:71], v[70:71]
	global_store_dwordx2 v[126:127], v[74:75], off offset:256
	v_pk_mov_b32 v[74:75], v[70:71], v[72:73] op_sel:[1,0]
	v_mov_b32_e32 v71, v73
	v_pk_add_f32 v[70:71], v[74:75], v[70:71]
	s_nop 0
	v_add_f32_e32 v70, v70, v71
	v_add_f32_e32 v132, v70, v132
.LBB0_166:
	v_pk_add_f32 v[68:69], v[68:69], v[116:117]
	v_pk_add_f32 v[66:67], v[66:67], v[114:115]
	s_and_b64 vcc, exec, s[6:7]
	s_mov_b64 s[36:37], 0
	global_store_dwordx4 v[128:129], v[66:69], off offset:576
	s_cbranch_vccnz .LBB0_168
	v_cvt_pk_bf16_f32 v70, v66, v67
	v_cvt_pk_bf16_f32 v71, v68, v69
	s_nop 0
	v_pk_mul_f32 v[68:69], v[68:69], v[68:69]
	v_pk_mul_f32 v[66:67], v[66:67], v[66:67]
	global_store_dwordx2 v[126:127], v[70:71], off offset:288
	v_pk_mov_b32 v[70:71], v[66:67], v[68:69] op_sel:[1,0]
	v_mov_b32_e32 v67, v69
	v_pk_add_f32 v[66:67], v[70:71], v[66:67]
	s_mov_b64 s[36:37], s[14:15]
	v_add_f32_e32 v66, v66, v67
	v_add_f32_e32 v132, v66, v132
.LBB0_168:
	s_cmp_eq_u64 s[36:37], 0
	s_cbranch_scc1 .LBB0_172
	v_and_b32_e32 v67, 64, v204
	v_xor_b32_e32 v66, 16, v204
	v_add_u32_e32 v67, 64, v67
	v_cmp_lt_i32_e32 vcc, v66, v67
	v_xor_b32_e32 v68, 32, v204
	s_nop 0
	v_cndmask_b32_e32 v66, v204, v66, vcc
	v_lshlrev_b32_e32 v66, 2, v66
	ds_bpermute_b32 v66, v66, v132
	v_cmp_lt_i32_e32 vcc, v68, v67
	s_waitcnt lgkmcnt(0)
	v_add_f32_e32 v66, v132, v66
	v_cndmask_b32_e32 v67, v204, v68, vcc
	v_lshlrev_b32_e32 v67, 2, v67
	ds_bpermute_b32 v67, v67, v66
	s_and_saveexec_b64 s[38:39], s[8:9]
	s_cbranch_execz .LBB0_171
	v_lshl_add_u64 v[68:69], v[190:191], 2, s[36:37]
	s_waitcnt lgkmcnt(0)
	v_add_f32_e32 v66, v66, v67
	global_atomic_add_f32 v[68:69], v66, off offset:192

; #define EO_LOAD(rr, slot) do { const size_t o_ = (size_t)(row0 + ((rr) >> 2) * 128 + ((rr) & 3) * 16) * DM + col0; _Pragma("unroll") for (int q_ = 0; q_ < 4; ++q_) xr[slot][q_] = *(const f32x4*)(Xin + o_ + (q_ >> 1) * 128 + (q_ & 1) * 16); } while (0)
;     __device__ __forceinline__ void operator()(const f32x4 (&acc)[2][2][4][2], const pg8::Unit& u, int wr, int wc, int fr, int fq) const {
;     ...
;         EO_LOAD(0, 0); EO_LOAD(1, 1);
; #pragma unroll
;         for (int rr = 0; rr < 8; ++rr) { const int ai = rr >> 2, m = rr & 3, row = row0 + ai * 128 + m * 16; const size_t o = (size_t)row * DM + col0; float s = 0.f;
;             if (rr + 2 < 8) EO_LOAD(rr + 2, (rr + 2) % 3);
.LBB0_172:
	v_add_u32_e32 v114, 0xa0, v190
	v_ashrrev_i32_e32 v115, 31, v114
	s_waitcnt lgkmcnt(0)
	v_lshlrev_b64 v[66:67], 13, v[114:115]
	v_lshl_add_u64 v[66:67], s[10:11], 0, v[66:67]
	v_lshl_add_u64 v[66:67], v[192:193], 2, v[66:67]
	global_load_dwordx4 v[78:81], v[66:67], off
	global_load_dwordx4 v[74:77], v[66:67], off offset:64
	global_load_dwordx4 v[70:73], v[66:67], off offset:512
	s_nop 0
	global_load_dwordx4 v[66:69], v[66:67], off offset:576
	v_lshlrev_b64 v[116:117], 11, v[146:147]
	v_readlane_b32 s72, v251, 6
	v_lshl_add_u64 v[118:119], v[116:117], 0, v[192:193]
	v_readlane_b32 s86, v251, 20
	v_readlane_b32 s87, v251, 21
	s_cmp_eq_u64 s[12:13], 0
	s_cbranch_scc1 .Lmy_eo_r4_n
	s_waitcnt vmcnt(26)
	s_branch .Lmy_eo_r4_d

; __device__ __forceinline__ unsigned cvt_pk_bf16(float lo, float hi) { unsigned r; asm volatile("v_cvt_pk_bf16_f32 %0, %1, %2" : "=v"(r) : "v"(lo), "v"(hi)); return r; }
; #define EO_LOAD(rr, slot) do { const size_t o_ = (size_t)(row0 + ((rr) >> 2) * 128 + ((rr) & 3) * 16) * DM + col0; _Pragma("unroll") for (int q_ = 0; q_ < 4; ++q_) xr[slot][q_] = *(const f32x4*)(Xin + o_ + (q_ >> 1) * 128 + (q_ & 1) * 16); } while (0)
;     __device__ __forceinline__ void operator()(const f32x4 (&acc)[2][2][4][2], const pg8::Unit& u, int wr, int wc, int fr, int fq) const {
;     ...
;         for (int rr = 0; rr < 8; ++rr) { const int ai = rr >> 2, m = rr & 3, row = row0 + ai * 128 + m * 16; const size_t o = (size_t)row * DM + col0; float s = 0.f;
;             if (rr + 2 < 8) EO_LOAD(rr + 2, (rr + 2) % 3);
; #pragma unroll
;             for (int q = 0; q < 4; ++q) { const int bj = q >> 1, n = q & 1; const size_t idx = o + bj * 128 + n * 16; const f32x4 v = xr[rr % 3][q] + acc[ai][bj][m][n]; *(f32x4*)(Out + idx) = v;
;                 if (ssq) { u32x2 w; w.x = cvt_pk_bf16(v[0], v[1]); w.y = cvt_pk_bf16(v[2], v[3]); *(u32x2*)(HBo + idx) = w; s += (v[0] * v[0] + v[1] * v[1]) + (v[2] * v[2] + v[3] * v[3]); } }
;             if (ssq) { s += __shfl_xor(s, 16); s += __shfl_xor(s, 32); if (fq == 0) atomicAdd(ssq + row, s); } }
.Lmy_eo_r4_d:
	v_pk_add_f32 v[64:65], v[64:65], v[112:113]
	v_pk_add_f32 v[62:63], v[62:63], v[110:111]
	v_lshl_add_u64 v[112:113], v[118:119], 2, s[86:87]
	v_mov_b32_e32 v116, 0
	s_and_b64 vcc, exec, s[6:7]
	v_lshl_add_u64 v[110:111], v[118:119], 1, s[22:23]
	v_readlane_b32 s73, v251, 7
	v_readlane_b32 s74, v251, 8
	v_readlane_b32 s75, v251, 9
	v_readlane_b32 s76, v251, 10
	v_readlane_b32 s77, v251, 11
	v_readlane_b32 s78, v251, 12
	v_readlane_b32 s79, v251, 13
	v_readlane_b32 s80, v251, 14
	v_readlane_b32 s81, v251, 15
	v_readlane_b32 s82, v251, 16
	v_readlane_b32 s83, v251, 17
	v_readlane_b32 s84, v251, 18
	v_readlane_b32 s85, v251, 19
	global_store_dwordx4 v[112:113], v[62:65], off
	s_cbranch_vccnz .LBB0_174
	v_cvt_pk_bf16_f32 v116, v62, v63
	v_cvt_pk_bf16_f32 v117, v64, v65
	s_nop 0
	v_pk_mul_f32 v[64:65], v[64:65], v[64:65]
	v_pk_mul_f32 v[62:63], v[62:63], v[62:63]
	global_store_dwordx2 v[110:111], v[116:117], off
	v_pk_mov_b32 v[116:117], v[62:63], v[64:65] op_sel:[1,0]
	v_mov_b32_e32 v63, v65
	v_pk_add_f32 v[62:63], v[116:117], v[62:63]
	s_nop 0
	v_add_f32_e32 v116, v62, v63
.LBB0_174:
	v_pk_add_f32 v[60:61], v[60:61], v[108:109]
	v_pk_add_f32 v[58:59], v[58:59], v[106:107]
	s_and_b64 vcc, exec, s[6:7]
	global_store_dwordx4 v[112:113], v[58:61], off offset:64
	s_cbranch_vccnz .LBB0_176
	v_cvt_pk_bf16_f32 v62, v58, v59
	v_cvt_pk_bf16_f32 v63, v60, v61
	s_nop 0
	v_pk_mul_f32 v[60:61], v[60:61], v[60:61]
	v_pk_mul_f32 v[58:59], v[58:59], v[58:59]
	global_store_dwordx2 v[110:111], v[62:63], off offset:32
	v_pk_mov_b32 v[62:63], v[58:59], v[60:61] op_sel:[1,0]
	v_mov_b32_e32 v59, v61
	v_pk_add_f32 v[58:59], v[62:63], v[58:59]
	s_nop 0
	v_add_f32_e32 v58, v58, v59
	v_add_f32_e32 v116, v58, v116
.LBB0_176:
	v_pk_add_f32 v[56:57], v[56:57], v[104:105]
	v_pk_add_f32 v[54:55], v[54:55], v[102:103]
	s_and_b64 vcc, exec, s[6:7]
	global_store_dwordx4 v[112:113], v[54:57], off offset:512
	s_cbranch_vccnz .LBB0_178
	v_cvt_pk_bf16_f32 v58, v54, v55
	v_cvt_pk_bf16_f32 v59, v56, v57
	s_nop 0
	v_pk_mul_f32 v[56:57], v[56:57], v[56:57]
	v_pk_mul_f32 v[54:55], v[54:55], v[54:55]
	global_store_dwordx2 v[110:111], v[58:59], off offset:256
	v_pk_mov_b32 v[58:59], v[54:55], v[56:57] op_sel:[1,0]
	v_mov_b32_e32 v55, v57
	v_pk_add_f32 v[54:55], v[58:59], v[54:55]
	s_nop 0
	v_add_f32_e32 v54, v54, v55
	v_add_f32_e32 v116, v54, v116
.LBB0_178:
	v_pk_add_f32 v[52:53], v[52:53], v[100:101]
	v_pk_add_f32 v[50:51], v[50:51], v[98:99]
	s_and_b64 vcc, exec, s[6:7]
	s_mov_b64 s[36:37], 0
	global_store_dwordx4 v[112:113], v[50:53], off offset:576
	s_cbranch_vccnz .LBB0_180
	v_cvt_pk_bf16_f32 v54, v50, v51
	v_cvt_pk_bf16_f32 v55, v52, v53
	s_nop 0
	v_pk_mul_f32 v[52:53], v[52:53], v[52:53]
	v_pk_mul_f32 v[50:51], v[50:51], v[50:51]
	global_store_dwordx2 v[110:111], v[54:55], off offset:288
	v_pk_mov_b32 v[54:55], v[50:51], v[52:53] op_sel:[1,0]
	v_mov_b32_e32 v51, v53
	v_pk_add_f32 v[50:51], v[54:55], v[50:51]
	s_mov_b64 s[36:37], s[14:15]
	v_add_f32_e32 v50, v50, v51
	v_add_f32_e32 v116, v50, v116
.LBB0_180:
	s_cmp_eq_u64 s[36:37], 0
	s_cbranch_scc1 .LBB0_184
	v_and_b32_e32 v51, 64, v204
	v_xor_b32_e32 v50, 16, v204
	v_add_u32_e32 v51, 64, v51
	v_cmp_lt_i32_e32 vcc, v50, v51
	v_xor_b32_e32 v52, 32, v204
	s_nop 0
	v_cndmask_b32_e32 v50, v204, v50, vcc
	v_lshlrev_b32_e32 v50, 2, v50
	ds_bpermute_b32 v50, v50, v116
	v_cmp_lt_i32_e32 vcc, v52, v51
	s_waitcnt lgkmcnt(0)
	v_add_f32_e32 v50, v116, v50
	v_cndmask_b32_e32 v51, v204, v52, vcc
	v_lshlrev_b32_e32 v51, 2, v51
	ds_bpermute_b32 v51, v51, v50
	s_and_saveexec_b64 s[38:39], s[8:9]
	s_cbranch_execz .LBB0_183
	v_lshl_add_u64 v[52:53], v[190:191], 2, s[36:37]
	s_waitcnt lgkmcnt(0)
	v_add_f32_e32 v50, v50, v51
	global_atomic_add_f32 v[52:53], v50, off offset:512

; #define EO_LOAD(rr, slot) do { const size_t o_ = (size_t)(row0 + ((rr) >> 2) * 128 + ((rr) & 3) * 16) * DM + col0; _Pragma("unroll") for (int q_ = 0; q_ < 4; ++q_) xr[slot][q_] = *(const f32x4*)(Xin + o_ + (q_ >> 1) * 128 + (q_ & 1) * 16); } while (0)
;     __device__ __forceinline__ void operator()(const f32x4 (&acc)[2][2][4][2], const pg8::Unit& u, int wr, int wc, int fr, int fq) const {
;     ...
;         EO_LOAD(0, 0); EO_LOAD(1, 1);
; #pragma unroll
;         for (int rr = 0; rr < 8; ++rr) { const int ai = rr >> 2, m = rr & 3, row = row0 + ai * 128 + m * 16; const size_t o = (size_t)row * DM + col0; float s = 0.f;
;             if (rr + 2 < 8) EO_LOAD(rr + 2, (rr + 2) % 3);
.LBB0_184:
	v_add_u32_e32 v98, 0xb0, v190
	v_ashrrev_i32_e32 v99, 31, v98
	s_waitcnt lgkmcnt(0)
	v_lshlrev_b64 v[50:51], 13, v[98:99]
	v_lshl_add_u64 v[50:51], s[10:11], 0, v[50:51]
	v_lshl_add_u64 v[50:51], v[192:193], 2, v[50:51]
	global_load_dwordx4 v[62:65], v[50:51], off
	global_load_dwordx4 v[58:61], v[50:51], off offset:64
	global_load_dwordx4 v[54:57], v[50:51], off offset:512
	s_nop 0
	global_load_dwordx4 v[50:53], v[50:51], off offset:576
	v_lshlrev_b64 v[100:101], 11, v[130:131]
	v_readlane_b32 s72, v251, 6
	v_lshl_add_u64 v[102:103], v[100:101], 0, v[192:193]
	v_readlane_b32 s86, v251, 20
	v_readlane_b32 s87, v251, 21
	s_cmp_eq_u64 s[12:13], 0
	s_cbranch_scc1 .Lmy_eo_r5_n
	s_waitcnt vmcnt(26)
	s_branch .Lmy_eo_r5_d

; __device__ __forceinline__ unsigned cvt_pk_bf16(float lo, float hi) { unsigned r; asm volatile("v_cvt_pk_bf16_f32 %0, %1, %2" : "=v"(r) : "v"(lo), "v"(hi)); return r; }
; #define EO_LOAD(rr, slot) do { const size_t o_ = (size_t)(row0 + ((rr) >> 2) * 128 + ((rr) & 3) * 16) * DM + col0; _Pragma("unroll") for (int q_ = 0; q_ < 4; ++q_) xr[slot][q_] = *(const f32x4*)(Xin + o_ + (q_ >> 1) * 128 + (q_ & 1) * 16); } while (0)
;     __device__ __forceinline__ void operator()(const f32x4 (&acc)[2][2][4][2], const pg8::Unit& u, int wr, int wc, int fr, int fq) const {
;     ...
;         for (int rr = 0; rr < 8; ++rr) { const int ai = rr >> 2, m = rr & 3, row = row0 + ai * 128 + m * 16; const size_t o = (size_t)row * DM + col0; float s = 0.f;
;             if (rr + 2 < 8) EO_LOAD(rr + 2, (rr + 2) % 3);
; #pragma unroll
;             for (int q = 0; q < 4; ++q) { const int bj = q >> 1, n = q & 1; const size_t idx = o + bj * 128 + n * 16; const f32x4 v = xr[rr % 3][q] + acc[ai][bj][m][n]; *(f32x4*)(Out + idx) = v;
;                 if (ssq) { u32x2 w; w.x = cvt_pk_bf16(v[0], v[1]); w.y = cvt_pk_bf16(v[2], v[3]); *(u32x2*)(HBo + idx) = w; s += (v[0] * v[0] + v[1] * v[1]) + (v[2] * v[2] + v[3] * v[3]); } }
;             if (ssq) { s += __shfl_xor(s, 16); s += __shfl_xor(s, 32); if (fq == 0) atomicAdd(ssq + row, s); } }
.Lmy_eo_r5_d:
	v_pk_add_f32 v[48:49], v[48:49], v[96:97]
	v_pk_add_f32 v[46:47], v[46:47], v[94:95]
	v_lshl_add_u64 v[96:97], v[102:103], 2, s[86:87]
	v_mov_b32_e32 v100, 0
	s_and_b64 vcc, exec, s[6:7]
	v_lshl_add_u64 v[94:95], v[102:103], 1, s[22:23]
	v_readlane_b32 s73, v251, 7
	v_readlane_b32 s74, v251, 8
	v_readlane_b32 s75, v251, 9
	v_readlane_b32 s76, v251, 10
	v_readlane_b32 s77, v251, 11
	v_readlane_b32 s78, v251, 12
	v_readlane_b32 s79, v251, 13
	v_readlane_b32 s80, v251, 14
	v_readlane_b32 s81, v251, 15
	v_readlane_b32 s82, v251, 16
	v_readlane_b32 s83, v251, 17
	v_readlane_b32 s84, v251, 18
	v_readlane_b32 s85, v251, 19
	global_store_dwordx4 v[96:97], v[46:49], off
	s_cbranch_vccnz .LBB0_186
	v_cvt_pk_bf16_f32 v100, v46, v47
	v_cvt_pk_bf16_f32 v101, v48, v49
	s_nop 0
	v_pk_mul_f32 v[48:49], v[48:49], v[48:49]
	v_pk_mul_f32 v[46:47], v[46:47], v[46:47]
	global_store_dwordx2 v[94:95], v[100:101], off
	v_pk_mov_b32 v[100:101], v[46:47], v[48:49] op_sel:[1,0]
	v_mov_b32_e32 v47, v49
	v_pk_add_f32 v[46:47], v[100:101], v[46:47]
	s_nop 0
	v_add_f32_e32 v100, v46, v47
.LBB0_186:
	v_pk_add_f32 v[44:45], v[44:45], v[92:93]
	v_pk_add_f32 v[42:43], v[42:43], v[90:91]
	s_and_b64 vcc, exec, s[6:7]
	global_store_dwordx4 v[96:97], v[42:45], off offset:64
	s_cbranch_vccnz .LBB0_188
	v_cvt_pk_bf16_f32 v46, v42, v43
	v_cvt_pk_bf16_f32 v47, v44, v45
	s_nop 0
	v_pk_mul_f32 v[44:45], v[44:45], v[44:45]
	v_pk_mul_f32 v[42:43], v[42:43], v[42:43]
	global_store_dwordx2 v[94:95], v[46:47], off offset:32
	v_pk_mov_b32 v[46:47], v[42:43], v[44:45] op_sel:[1,0]
	v_mov_b32_e32 v43, v45
	v_pk_add_f32 v[42:43], v[46:47], v[42:43]
	s_nop 0
	v_add_f32_e32 v42, v42, v43
	v_add_f32_e32 v100, v42, v100
.LBB0_188:
	v_pk_add_f32 v[40:41], v[40:41], v[88:89]
	v_pk_add_f32 v[38:39], v[38:39], v[86:87]
	s_and_b64 vcc, exec, s[6:7]
	global_store_dwordx4 v[96:97], v[38:41], off offset:512
	s_cbranch_vccnz .LBB0_190
	v_cvt_pk_bf16_f32 v42, v38, v39
	v_cvt_pk_bf16_f32 v43, v40, v41
	s_nop 0
	v_pk_mul_f32 v[40:41], v[40:41], v[40:41]
	v_pk_mul_f32 v[38:39], v[38:39], v[38:39]
	global_store_dwordx2 v[94:95], v[42:43], off offset:256
	v_pk_mov_b32 v[42:43], v[38:39], v[40:41] op_sel:[1,0]
	v_mov_b32_e32 v39, v41
	v_pk_add_f32 v[38:39], v[42:43], v[38:39]
	s_nop 0
	v_add_f32_e32 v38, v38, v39
	v_add_f32_e32 v100, v38, v100
.LBB0_190:
	v_pk_add_f32 v[36:37], v[36:37], v[84:85]
	v_pk_add_f32 v[34:35], v[34:35], v[82:83]
	s_and_b64 vcc, exec, s[6:7]
	s_mov_b64 s[36:37], 0
	global_store_dwordx4 v[96:97], v[34:37], off offset:576
	s_cbranch_vccnz .LBB0_192
	v_cvt_pk_bf16_f32 v38, v34, v35
	v_cvt_pk_bf16_f32 v39, v36, v37
	s_nop 0
	v_pk_mul_f32 v[36:37], v[36:37], v[36:37]
	v_pk_mul_f32 v[34:35], v[34:35], v[34:35]
	global_store_dwordx2 v[94:95], v[38:39], off offset:288
	v_pk_mov_b32 v[38:39], v[34:35], v[36:37] op_sel:[1,0]
	v_mov_b32_e32 v35, v37
	v_pk_add_f32 v[34:35], v[38:39], v[34:35]
	s_mov_b64 s[36:37], s[14:15]
	v_add_f32_e32 v34, v34, v35
	v_add_f32_e32 v100, v34, v100
.LBB0_192:
	s_cmp_eq_u64 s[36:37], 0
	s_cbranch_scc1 .LBB0_196
	v_and_b32_e32 v35, 64, v204
	v_xor_b32_e32 v34, 16, v204
	v_add_u32_e32 v35, 64, v35
	v_cmp_lt_i32_e32 vcc, v34, v35
	v_xor_b32_e32 v36, 32, v204
	s_nop 0
	v_cndmask_b32_e32 v34, v204, v34, vcc
	v_lshlrev_b32_e32 v34, 2, v34
	ds_bpermute_b32 v34, v34, v100
	v_cmp_lt_i32_e32 vcc, v36, v35
	s_waitcnt lgkmcnt(0)
	v_add_f32_e32 v34, v100, v34
	v_cndmask_b32_e32 v35, v204, v36, vcc
	v_lshlrev_b32_e32 v35, 2, v35
	ds_bpermute_b32 v35, v35, v34
	s_and_saveexec_b64 s[38:39], s[8:9]
	s_cbranch_execz .LBB0_195
	v_lshl_add_u64 v[36:37], v[190:191], 2, s[36:37]
	s_waitcnt lgkmcnt(0)
	v_add_f32_e32 v34, v34, v35
	global_atomic_add_f32 v[36:37], v34, off offset:576

; #define EO_LOAD(rr, slot) do { const size_t o_ = (size_t)(row0 + ((rr) >> 2) * 128 + ((rr) & 3) * 16) * DM + col0; _Pragma("unroll") for (int q_ = 0; q_ < 4; ++q_) xr[slot][q_] = *(const f32x4*)(Xin + o_ + (q_ >> 1) * 128 + (q_ & 1) * 16); } while (0)
;     __device__ __forceinline__ void operator()(const f32x4 (&acc)[2][2][4][2], const pg8::Unit& u, int wr, int wc, int fr, int fq) const {
;     ...
;         EO_LOAD(0, 0); EO_LOAD(1, 1);
; #pragma unroll
;         for (int rr = 0; rr < 8; ++rr) { const int ai = rr >> 2, m = rr & 3, row = row0 + ai * 128 + m * 16; const size_t o = (size_t)row * DM + col0; float s = 0.f;
;             if (rr + 2 < 8) EO_LOAD(rr + 2, (rr + 2) % 3);
.LBB0_196:
	s_waitcnt lgkmcnt(0)
	v_lshlrev_b64 v[34:35], 11, v[114:115]
	v_readlane_b32 s72, v251, 6
	v_lshl_add_u64 v[34:35], v[34:35], 0, v[192:193]
	v_readlane_b32 s86, v251, 20
	v_readlane_b32 s87, v251, 21
	s_cmp_eq_u64 s[12:13], 0
	s_cbranch_scc1 .Lmy_eo_r6_n
	s_waitcnt vmcnt(22)
	s_branch .Lmy_eo_r6_d

; __device__ __forceinline__ unsigned cvt_pk_bf16(float lo, float hi) { unsigned r; asm volatile("v_cvt_pk_bf16_f32 %0, %1, %2" : "=v"(r) : "v"(lo), "v"(hi)); return r; }
; #define EO_LOAD(rr, slot) do { const size_t o_ = (size_t)(row0 + ((rr) >> 2) * 128 + ((rr) & 3) * 16) * DM + col0; _Pragma("unroll") for (int q_ = 0; q_ < 4; ++q_) xr[slot][q_] = *(const f32x4*)(Xin + o_ + (q_ >> 1) * 128 + (q_ & 1) * 16); } while (0)
;     __device__ __forceinline__ void operator()(const f32x4 (&acc)[2][2][4][2], const pg8::Unit& u, int wr, int wc, int fr, int fq) const {
;     ...
;         for (int rr = 0; rr < 8; ++rr) { const int ai = rr >> 2, m = rr & 3, row = row0 + ai * 128 + m * 16; const size_t o = (size_t)row * DM + col0; float s = 0.f;
;             if (rr + 2 < 8) EO_LOAD(rr + 2, (rr + 2) % 3);
; #pragma unroll
;             for (int q = 0; q < 4; ++q) { const int bj = q >> 1, n = q & 1; const size_t idx = o + bj * 128 + n * 16; const f32x4 v = xr[rr % 3][q] + acc[ai][bj][m][n]; *(f32x4*)(Out + idx) = v;
;                 if (ssq) { u32x2 w; w.x = cvt_pk_bf16(v[0], v[1]); w.y = cvt_pk_bf16(v[2], v[3]); *(u32x2*)(HBo + idx) = w; s += (v[0] * v[0] + v[1] * v[1]) + (v[2] * v[2] + v[3] * v[3]); } }
;             if (ssq) { s += __shfl_xor(s, 16); s += __shfl_xor(s, 32); if (fq == 0) atomicAdd(ssq + row, s); } }
.Lmy_eo_r6_d:
	v_pk_add_f32 v[32:33], v[32:33], v[80:81]
	v_pk_add_f32 v[30:31], v[30:31], v[78:79]
	v_lshl_add_u64 v[36:37], v[34:35], 2, s[86:87]
	v_mov_b32_e32 v38, 0
	s_and_b64 vcc, exec, s[6:7]
	v_lshl_add_u64 v[34:35], v[34:35], 1, s[22:23]
	v_readlane_b32 s73, v251, 7
	v_readlane_b32 s74, v251, 8
	v_readlane_b32 s75, v251, 9
	v_readlane_b32 s76, v251, 10
	v_readlane_b32 s77, v251, 11
	v_readlane_b32 s78, v251, 12
	v_readlane_b32 s79, v251, 13
	v_readlane_b32 s80, v251, 14
	v_readlane_b32 s81, v251, 15
	v_readlane_b32 s82, v251, 16
	v_readlane_b32 s83, v251, 17
	v_readlane_b32 s84, v251, 18
	v_readlane_b32 s85, v251, 19
	global_store_dwordx4 v[36:37], v[30:33], off
	s_cbranch_vccnz .LBB0_198
	v_cvt_pk_bf16_f32 v38, v30, v31
	v_cvt_pk_bf16_f32 v39, v32, v33
	s_nop 0
	v_pk_mul_f32 v[32:33], v[32:33], v[32:33]
	v_pk_mul_f32 v[30:31], v[30:31], v[30:31]
	global_store_dwordx2 v[34:35], v[38:39], off
	v_pk_mov_b32 v[38:39], v[30:31], v[32:33] op_sel:[1,0]
	v_mov_b32_e32 v31, v33
	v_pk_add_f32 v[30:31], v[38:39], v[30:31]
	s_nop 0
	v_add_f32_e32 v38, v30, v31
.LBB0_198:
	v_pk_add_f32 v[28:29], v[28:29], v[76:77]
	v_pk_add_f32 v[26:27], v[26:27], v[74:75]
	s_and_b64 vcc, exec, s[6:7]
	global_store_dwordx4 v[36:37], v[26:29], off offset:64
	s_cbranch_vccnz .LBB0_200
	v_cvt_pk_bf16_f32 v30, v26, v27
	v_cvt_pk_bf16_f32 v31, v28, v29
	s_nop 0
	v_pk_mul_f32 v[28:29], v[28:29], v[28:29]
	v_pk_mul_f32 v[26:27], v[26:27], v[26:27]
	global_store_dwordx2 v[34:35], v[30:31], off offset:32
	v_pk_mov_b32 v[30:31], v[26:27], v[28:29] op_sel:[1,0]
	v_mov_b32_e32 v27, v29
	v_pk_add_f32 v[26:27], v[30:31], v[26:27]
	s_nop 0
	v_add_f32_e32 v26, v26, v27
	v_add_f32_e32 v38, v26, v38
.LBB0_200:
	v_pk_add_f32 v[24:25], v[24:25], v[72:73]
	v_pk_add_f32 v[22:23], v[22:23], v[70:71]
	s_and_b64 vcc, exec, s[6:7]
	global_store_dwordx4 v[36:37], v[22:25], off offset:512
	s_cbranch_vccnz .LBB0_202
	v_cvt_pk_bf16_f32 v26, v22, v23
	v_cvt_pk_bf16_f32 v27, v24, v25
	s_nop 0
	v_pk_mul_f32 v[24:25], v[24:25], v[24:25]
	v_pk_mul_f32 v[22:23], v[22:23], v[22:23]
	global_store_dwordx2 v[34:35], v[26:27], off offset:256
	v_pk_mov_b32 v[26:27], v[22:23], v[24:25] op_sel:[1,0]
	v_mov_b32_e32 v23, v25
	v_pk_add_f32 v[22:23], v[26:27], v[22:23]
	s_nop 0
	v_add_f32_e32 v22, v22, v23
	v_add_f32_e32 v38, v22, v38
.LBB0_202:
	v_pk_add_f32 v[20:21], v[20:21], v[68:69]
	v_pk_add_f32 v[18:19], v[18:19], v[66:67]
	s_and_b64 vcc, exec, s[6:7]
	s_mov_b64 s[36:37], 0
	global_store_dwordx4 v[36:37], v[18:21], off offset:576
	s_cbranch_vccnz .LBB0_204
	v_cvt_pk_bf16_f32 v22, v18, v19
	v_cvt_pk_bf16_f32 v23, v20, v21
	s_nop 0
	v_pk_mul_f32 v[20:21], v[20:21], v[20:21]
	v_pk_mul_f32 v[18:19], v[18:19], v[18:19]
	global_store_dwordx2 v[34:35], v[22:23], off offset:288
	v_pk_mov_b32 v[22:23], v[18:19], v[20:21] op_sel:[1,0]
	v_mov_b32_e32 v19, v21
	v_pk_add_f32 v[18:19], v[22:23], v[18:19]
	s_mov_b64 s[36:37], s[14:15]
	v_add_f32_e32 v18, v18, v19
	v_add_f32_e32 v38, v18, v38
.LBB0_204:
	s_cmp_eq_u64 s[36:37], 0
	s_cbranch_scc1 .LBB0_208
	v_and_b32_e32 v19, 64, v204
	v_xor_b32_e32 v18, 16, v204
	v_add_u32_e32 v19, 64, v19
	v_cmp_lt_i32_e32 vcc, v18, v19
	v_xor_b32_e32 v20, 32, v204
	s_nop 0
	v_cndmask_b32_e32 v18, v204, v18, vcc
	v_lshlrev_b32_e32 v18, 2, v18
	ds_bpermute_b32 v18, v18, v38
	v_cmp_lt_i32_e32 vcc, v20, v19
	s_waitcnt lgkmcnt(0)
	v_add_f32_e32 v18, v38, v18
	v_cndmask_b32_e32 v19, v204, v20, vcc
	v_lshlrev_b32_e32 v19, 2, v19
	ds_bpermute_b32 v19, v19, v18
	s_and_saveexec_b64 s[38:39], s[8:9]
	s_cbranch_execz .LBB0_207
	v_lshl_add_u64 v[20:21], v[190:191], 2, s[36:37]
	s_waitcnt lgkmcnt(0)
	v_add_f32_e32 v18, v18, v19
	global_atomic_add_f32 v[20:21], v18, off offset:640

; __device__ __forceinline__ unsigned cvt_pk_bf16(float lo, float hi) { unsigned r; asm volatile("v_cvt_pk_bf16_f32 %0, %1, %2" : "=v"(r) : "v"(lo), "v"(hi)); return r; }
; #define EO_LOAD(rr, slot) do { const size_t o_ = (size_t)(row0 + ((rr) >> 2) * 128 + ((rr) & 3) * 16) * DM + col0; _Pragma("unroll") for (int q_ = 0; q_ < 4; ++q_) xr[slot][q_] = *(const f32x4*)(Xin + o_ + (q_ >> 1) * 128 + (q_ & 1) * 16); } while (0)
;     __device__ __forceinline__ void operator()(const f32x4 (&acc)[2][2][4][2], const pg8::Unit& u, int wr, int wc, int fr, int fq) const {
;     ...
;         EO_LOAD(0, 0); EO_LOAD(1, 1);
; #pragma unroll
;         for (int rr = 0; rr < 8; ++rr) { const int ai = rr >> 2, m = rr & 3, row = row0 + ai * 128 + m * 16; const size_t o = (size_t)row * DM + col0; float s = 0.f;
;             if (rr + 2 < 8) EO_LOAD(rr + 2, (rr + 2) % 3);
; #pragma unroll
;             for (int q = 0; q < 4; ++q) { const int bj = q >> 1, n = q & 1; const size_t idx = o + bj * 128 + n * 16; const f32x4 v = xr[rr % 3][q] + acc[ai][bj][m][n]; *(f32x4*)(Out + idx) = v;
;                 if (ssq) { u32x2 w; w.x = cvt_pk_bf16(v[0], v[1]); w.y = cvt_pk_bf16(v[2], v[3]); *(u32x2*)(HBo + idx) = w; s += (v[0] * v[0] + v[1] * v[1]) + (v[2] * v[2] + v[3] * v[3]); } }
;             if (ssq) { s += __shfl_xor(s, 16); s += __shfl_xor(s, 32); if (fq == 0) atomicAdd(ssq + row, s); } }
.LBB0_208:
	s_waitcnt lgkmcnt(0)
	v_lshlrev_b64 v[18:19], 11, v[98:99]
	v_readlane_b32 s72, v251, 6
	v_lshl_add_u64 v[18:19], v[18:19], 0, v[192:193]
	v_readlane_b32 s86, v251, 20
	v_readlane_b32 s87, v251, 21
	s_cmp_eq_u64 s[12:13], 0
	s_cbranch_scc1 .Lmy_eo_r7_n
	s_waitcnt vmcnt(18)
	s_branch .Lmy_eo_r7_d
.Lmy_eo_r7_n:
	s_waitcnt vmcnt(8)
.Lmy_eo_r7_d:
	v_pk_add_f32 v[16:17], v[16:17], v[64:65]
	v_pk_add_f32 v[14:15], v[14:15], v[62:63]
	v_lshl_add_u64 v[20:21], v[18:19], 2, s[86:87]
	v_mov_b32_e32 v22, 0
	s_and_b64 vcc, exec, s[6:7]
	v_lshl_add_u64 v[18:19], v[18:19], 1, s[22:23]
	v_readlane_b32 s73, v251, 7
	v_readlane_b32 s74, v251, 8
	v_readlane_b32 s75, v251, 9
	v_readlane_b32 s76, v251, 10
	v_readlane_b32 s77, v251, 11
	v_readlane_b32 s78, v251, 12
	v_readlane_b32 s79, v251, 13
	v_readlane_b32 s80, v251, 14
	v_readlane_b32 s81, v251, 15
	v_readlane_b32 s82, v251, 16
	v_readlane_b32 s83, v251, 17
	v_readlane_b32 s84, v251, 18
	v_readlane_b32 s85, v251, 19
	global_store_dwordx4 v[20:21], v[14:17], off
	s_cbranch_vccnz .LBB0_210
	v_cvt_pk_bf16_f32 v22, v14, v15
	v_cvt_pk_bf16_f32 v23, v16, v17
	s_nop 0
	v_pk_mul_f32 v[16:17], v[16:17], v[16:17]
	v_pk_mul_f32 v[14:15], v[14:15], v[14:15]
	global_store_dwordx2 v[18:19], v[22:23], off
	v_pk_mov_b32 v[22:23], v[14:15], v[16:17] op_sel:[1,0]
	v_mov_b32_e32 v15, v17
	v_pk_add_f32 v[14:15], v[22:23], v[14:15]
	s_nop 0
	v_add_f32_e32 v22, v14, v15
.LBB0_210:
	v_readlane_b32 s20, v250, 9
	v_pk_add_f32 v[12:13], v[12:13], v[60:61]
	v_pk_add_f32 v[10:11], v[10:11], v[58:59]
	s_and_b64 vcc, exec, s[6:7]
	v_readlane_b32 s21, v250, 10
	global_store_dwordx4 v[20:21], v[10:13], off offset:64
	s_cbranch_vccnz .LBB0_212
	v_cvt_pk_bf16_f32 v14, v10, v11
	v_cvt_pk_bf16_f32 v15, v12, v13
	s_nop 0
	v_pk_mul_f32 v[12:13], v[12:13], v[12:13]
	v_pk_mul_f32 v[10:11], v[10:11], v[10:11]
	global_store_dwordx2 v[18:19], v[14:15], off offset:32
	v_pk_mov_b32 v[14:15], v[10:11], v[12:13] op_sel:[1,0]
	v_mov_b32_e32 v11, v13
	v_pk_add_f32 v[10:11], v[14:15], v[10:11]
	s_nop 0
	v_add_f32_e32 v10, v10, v11
	v_add_f32_e32 v22, v10, v22
.LBB0_212:
	v_pk_add_f32 v[8:9], v[8:9], v[56:57]
	v_pk_add_f32 v[6:7], v[6:7], v[54:55]
	s_and_b64 vcc, exec, s[6:7]
	global_store_dwordx4 v[20:21], v[6:9], off offset:512
	s_cbranch_vccnz .LBB0_214
	v_cvt_pk_bf16_f32 v10, v6, v7
	v_cvt_pk_bf16_f32 v11, v8, v9
	s_nop 0
	v_pk_mul_f32 v[8:9], v[8:9], v[8:9]
	v_pk_mul_f32 v[6:7], v[6:7], v[6:7]
	global_store_dwordx2 v[18:19], v[10:11], off offset:256
	v_pk_mov_b32 v[10:11], v[6:7], v[8:9] op_sel:[1,0]
	v_mov_b32_e32 v7, v9
	v_pk_add_f32 v[6:7], v[10:11], v[6:7]
	s_nop 0
	v_add_f32_e32 v6, v6, v7
	v_add_f32_e32 v22, v6, v22
.LBB0_214:
	v_pk_add_f32 v[4:5], v[4:5], v[52:53]
	v_pk_add_f32 v[2:3], v[2:3], v[50:51]
	s_and_b64 vcc, exec, s[6:7]
	s_mov_b64 s[6:7], 0
	global_store_dwordx4 v[20:21], v[2:5], off offset:576
	s_cbranch_vccnz .LBB0_216
	v_cvt_pk_bf16_f32 v6, v2, v3
	v_cvt_pk_bf16_f32 v7, v4, v5
	s_nop 0
	v_pk_mul_f32 v[4:5], v[4:5], v[4:5]
	v_pk_mul_f32 v[2:3], v[2:3], v[2:3]
	global_store_dwordx2 v[18:19], v[6:7], off offset:288
	v_pk_mov_b32 v[6:7], v[2:3], v[4:5] op_sel:[1,0]
	v_mov_b32_e32 v3, v5
	v_pk_add_f32 v[2:3], v[6:7], v[2:3]
	s_mov_b64 s[6:7], s[14:15]
	v_add_f32_e32 v2, v2, v3
	v_add_f32_e32 v22, v2, v22
.LBB0_216:
	s_cmp_eq_u64 s[6:7], 0
	s_cbranch_scc1 .LBB0_220
	v_and_b32_e32 v3, 64, v204
	v_xor_b32_e32 v2, 16, v204
	v_add_u32_e32 v3, 64, v3
	v_cmp_lt_i32_e32 vcc, v2, v3
	v_xor_b32_e32 v4, 32, v204
	s_nop 0
	v_cndmask_b32_e32 v2, v204, v2, vcc
	v_lshlrev_b32_e32 v2, 2, v2
	ds_bpermute_b32 v2, v2, v22
	v_cmp_lt_i32_e32 vcc, v4, v3
	s_waitcnt lgkmcnt(0)
	v_add_f32_e32 v2, v22, v2
	v_cndmask_b32_e32 v3, v204, v4, vcc
	v_lshlrev_b32_e32 v3, 2, v3
	ds_bpermute_b32 v3, v3, v2
	s_and_saveexec_b64 s[36:37], s[8:9]
	s_cbranch_execz .LBB0_219
	v_lshl_add_u64 v[4:5], v[190:191], 2, s[6:7]
	s_waitcnt lgkmcnt(0)
	v_add_f32_e32 v2, v2, v3
	global_atomic_add_f32 v[4:5], v2, off offset:704

; template <class Epi, class Sched, bool ALIGN_EPI = false, bool SP2 = false>
; __device__ __forceinline__ void gemm_phase(PG8_LAS unsigned char* lds, const Gemm g, const Sched& S, const Epi& E, const int tid) {
;     ...
;         const bool has_next = S.next(ui + 1, nxt);
;         const char* nA = has_next ? (const char*)g.A + (size_t)nxt.pm * tstep : cA; const char* nB = has_next ? (const char*)g.Bt + (size_t)nxt.pn * tstep : cB;
;         for (int t = 0; t < nt; t += 2) {
;             const bool last = (t == nt - 2);
;             const char* a1 = cA + (size_t)(t + 1) * kstep;
;             const char* a2 = last ? nA : cA + (size_t)(t + 2) * kstep; const char* b2 = last ? nB : cB + (size_t)(t + 2) * kstep;
;             const char* a3 = a2 + kstep; const char* b3 = b2 + kstep;
;     ...
; #pragma unroll
;         for (int a = 0; a < 2; ++a)
; #pragma unroll
;             for (int b = 0; b < 2; ++b)
; #pragma unroll
;                 for (int m = 0; m < 4; ++m)
; #pragma unroll
;                     for (int n = 0; n < 2; ++n) acc[a][b][m][n] = (f32x4){0.f, 0.f, 0.f, 0.f};
;         cur = nxt; cA = nA; cB = nB; ++ui;
.LBB0_242:
	s_ashr_i32 s97, s96, 31
	s_lshl_b64 s[12:13], s[96:97], 20
	s_add_u32 s94, s56, s12
	s_addc_u32 s95, s57, s13
	s_and_b64 s[12:13], s[4:5], exec
	s_cselect_b32 s1, s95, s11
	s_cselect_b32 s7, s94, s10
	s_ashr_i32 s49, s48, 31
	s_lshl_b64 s[12:13], s[48:49], 20
	s_add_u32 s92, s28, s12
	s_addc_u32 s93, s29, s13
	s_and_b64 s[12:13], s[4:5], exec
	s_cselect_b32 s14, s93, s9
	s_cselect_b32 s15, s92, s8
	s_add_u32 s16, s8, 0x100
	s_addc_u32 s17, s9, 0
	s_add_u32 s8, s10, 0x80080
	v_mov_b32_e32 v66, 0
	s_addc_u32 s9, s11, 0
	s_mov_b32 s18, -2
	v_mov_b32_e32 v67, v66
	v_mov_b32_e32 v68, v66
	v_mov_b32_e32 v69, v66
	v_mov_b32_e32 v70, v66
	v_mov_b32_e32 v71, v66
	v_mov_b32_e32 v72, v66
	v_mov_b32_e32 v73, v66
	v_mov_b32_e32 v74, v66
	v_mov_b32_e32 v75, v66
	v_mov_b32_e32 v76, v66
	v_mov_b32_e32 v77, v66
	v_mov_b32_e32 v78, v66
	v_mov_b32_e32 v79, v66
	v_mov_b32_e32 v80, v66
	v_mov_b32_e32 v81, v66
	v_mov_b32_e32 v82, v66
	v_mov_b32_e32 v83, v66
	v_mov_b32_e32 v84, v66
	v_mov_b32_e32 v85, v66
	v_mov_b32_e32 v86, v66
	v_mov_b32_e32 v87, v66
	v_mov_b32_e32 v88, v66
	v_mov_b32_e32 v89, v66
	v_mov_b32_e32 v98, v66
	v_mov_b32_e32 v99, v66
	v_mov_b32_e32 v100, v66
	v_mov_b32_e32 v101, v66
	v_mov_b32_e32 v102, v66
	v_mov_b32_e32 v103, v66
	v_mov_b32_e32 v104, v66
	v_mov_b32_e32 v105, v66
	v_mov_b32_e32 v2, v66
	v_mov_b32_e32 v3, v66
	v_mov_b32_e32 v4, v66
	v_mov_b32_e32 v5, v66
	v_mov_b32_e32 v6, v66
	v_mov_b32_e32 v7, v66
	v_mov_b32_e32 v8, v66
	v_mov_b32_e32 v9, v66
	v_mov_b32_e32 v10, v66
	v_mov_b32_e32 v11, v66
	v_mov_b32_e32 v12, v66
	v_mov_b32_e32 v13, v66
	v_mov_b32_e32 v14, v66
	v_mov_b32_e32 v15, v66
	v_mov_b32_e32 v16, v66
	v_mov_b32_e32 v17, v66
	v_mov_b32_e32 v18, v66
	v_mov_b32_e32 v19, v66
	v_mov_b32_e32 v20, v66
	v_mov_b32_e32 v21, v66
	v_mov_b32_e32 v22, v66
	v_mov_b32_e32 v23, v66
	v_mov_b32_e32 v24, v66
	v_mov_b32_e32 v25, v66
	v_mov_b32_e32 v26, v66
	v_mov_b32_e32 v27, v66
	v_mov_b32_e32 v28, v66
	v_mov_b32_e32 v29, v66
	v_mov_b32_e32 v30, v66
	v_mov_b32_e32 v31, v66
	v_mov_b32_e32 v32, v66
	v_mov_b32_e32 v33, v66
	v_mov_b32_e32 v106, v66
	v_mov_b32_e32 v107, v66
	v_mov_b32_e32 v108, v66
	v_mov_b32_e32 v109, v66
	v_mov_b32_e32 v110, v66
	v_mov_b32_e32 v111, v66
	v_mov_b32_e32 v112, v66
	v_mov_b32_e32 v113, v66
	v_mov_b32_e32 v114, v66
	v_mov_b32_e32 v115, v66
	v_mov_b32_e32 v116, v66
	v_mov_b32_e32 v117, v66
	v_mov_b32_e32 v118, v66
	v_mov_b32_e32 v119, v66
	v_mov_b32_e32 v120, v66
	v_mov_b32_e32 v121, v66
	v_mov_b32_e32 v122, v66
	v_mov_b32_e32 v123, v66
	v_mov_b32_e32 v124, v66
	v_mov_b32_e32 v125, v66
	v_mov_b32_e32 v126, v66
	v_mov_b32_e32 v127, v66
	v_mov_b32_e32 v128, v66
	v_mov_b32_e32 v129, v66
	v_mov_b32_e32 v130, v66
	v_mov_b32_e32 v131, v66
	v_mov_b32_e32 v132, v66
	v_mov_b32_e32 v133, v66
	v_mov_b32_e32 v134, v66
	v_mov_b32_e32 v135, v66
	v_mov_b32_e32 v136, v66
	v_mov_b32_e32 v137, v66
	v_mov_b32_e32 v34, v66
	v_mov_b32_e32 v35, v66
	v_mov_b32_e32 v36, v66
	v_mov_b32_e32 v37, v66
	v_mov_b32_e32 v38, v66
	v_mov_b32_e32 v39, v66
	v_mov_b32_e32 v40, v66
	v_mov_b32_e32 v41, v66
	v_mov_b32_e32 v42, v66
	v_mov_b32_e32 v43, v66
	v_mov_b32_e32 v44, v66
	v_mov_b32_e32 v45, v66
	v_mov_b32_e32 v46, v66
	v_mov_b32_e32 v47, v66
	v_mov_b32_e32 v48, v66
	v_mov_b32_e32 v49, v66
	v_mov_b32_e32 v50, v66
	v_mov_b32_e32 v51, v66
	v_mov_b32_e32 v52, v66
	v_mov_b32_e32 v53, v66
	v_mov_b32_e32 v54, v66
	v_mov_b32_e32 v55, v66
	v_mov_b32_e32 v56, v66
	v_mov_b32_e32 v57, v66
	v_mov_b32_e32 v58, v66
	v_mov_b32_e32 v59, v66
	v_mov_b32_e32 v60, v66
	v_mov_b32_e32 v61, v66
	v_mov_b32_e32 v62, v66
	v_mov_b32_e32 v63, v66
	v_mov_b32_e32 v64, v66
	v_mov_b32_e32 v65, v66

;     __device__ __forceinline__ void operator()(const f32x4 (&acc)[2][2][4][2], const pg8::Unit& u, int wr, int wc, int fr, int fq) const {
;     ...
;         const int lrow0 = wr * 64 + fr, row0 = u.pm * 256 + lrow0, colt = u.pn * 256, pn = u.pn;
;         bf16_t* const Z = (bf16_t*)(ws + (kind == 3 ? WS_KVM : WS_Z)); float* const LS = (float*)(ws + WS_LS);
;         const float* const ssq = (kind == 3) ? nullptr : (const float*)(ws + WS_SSQ) + (size_t)L * NTOK;
;         const float* const gt = (const float*)(ws + WS_GT);
;         const float* const bfp = gt + 2048; const float* const gq = gt + 384 * L; const float* const gk = gq + 128; const float* const gm = (kind == 3) ? gt + 1536 : gq + 256;
;         if (kind == 1 && pn == 28) {
;             if (wc == 0) {
; #pragma unroll
;                 for (int ai = 0; ai < 2; ++ai)
; #pragma unroll
;                     for (int m = 0; m < 4; ++m) { const int row = row0 + ai * 128 + m * 16;
; #pragma unroll
;                         for (int n = 0; n < 2; ++n)
; #pragma unroll
;                             for (int j = 0; j < 4; ++j) { const int col = 8 * fq + 4 * n + j;
;                                 if (col < 12) { const float xv = acc[ai][0][m][n][j] * rsqrtf(ssq[row] * (1.f / DM) + EPS) + bfp[col]; LS[((size_t)(row >> 12) * 12 + col) * SEQ + (row & (SEQ - 1))] = fminf(xv, 0.f) - log1pf(expf(-fabsf(xv))); } } }
;             }
;             return;
;         }
;         int W = 0; const float* g = nullptr;
;         if (kind == 0) { if (pn == 12 || pn == 13) { W = 128; g = gm; } }
;         else if (kind == 3) { if ((pn & 3) < 2) { W = 128; g = gm + (pn >> 2) * 128; } }
;         else { if (pn < 6) { W = (kind == 1) ? 128 : 64; g = gq; } else if (pn < 12) { W = (kind == 1) ? 128 : 64; g = gk; } else if (pn == 18 || pn == 19) { W = 128; g = gm; } }
;         const bool act = (kind == 0) && (pn < 12);
;     ...
;             for (int m = 0; m < 4; ++m) rsv[m] = ssq ? rsqrtf(ssq[row0 + ai * 128 + m * 16] * (1.f / DM) + EPS) : 1.f;
.LBB0_246:
	v_mov_b32_e32 v0, v161
	v_mov_b32_e32 v179, v163
	s_cmp_eq_u32 s0, 28
	v_add_u32_e32 v0, s72, v0
	v_lshl_add_u32 v154, s6, 8, v0
	s_cselect_b64 s[6:7], -1, 0
	s_and_b64 s[6:7], s[86:87], s[6:7]
	s_andn2_b64 vcc, exec, s[6:7]
	s_mov_b64 s[6:7], -1
	s_cbranch_vccz .LBB0_506
	s_and_b64 vcc, exec, s[40:41]
	s_cbranch_vccz .Lmy_ez_nopre
	v_mov_b32_e32 v248, v154
	v_ashrrev_i32_e32 v249, 31, v154
	v_lshl_add_u64 v[248:249], v[248:249], 2, s[44:45]
	global_load_dword v240, v[248:249], off
	global_load_dword v241, v[248:249], off offset:64
	global_load_dword v242, v[248:249], off offset:128
	global_load_dword v243, v[248:249], off offset:192
	global_load_dword v244, v[248:249], off offset:512
	global_load_dword v245, v[248:249], off offset:576
	global_load_dword v246, v[248:249], off offset:640
	global_load_dword v247, v[248:249], off offset:704
.Lmy_ez_nopre:
	s_mov_b64 s[8:9], -1
	s_and_b64 vcc, exec, s[58:59]
	s_cbranch_vccz .LBB0_256
	s_and_b64 vcc, exec, s[40:41]
	s_cbranch_vccz .LBB0_253
	s_cmp_lt_i32 s0, 6
	v_readlane_b32 s1, v250, 41
	s_mov_b64 s[6:7], s[46:47]
	s_cbranch_scc1 .LBB0_252
	s_cmp_lt_u32 s0, 12
	v_readlane_b32 s1, v250, 41
	s_mov_b64 s[6:7], s[80:81]
	s_cbranch_scc1 .LBB0_252
	s_and_b32 s1, s0, 0x7ffffffe
	s_cmp_eq_u32 s1, 18
	v_readlane_b32 s1, v250, 40
	s_cselect_b32 s7, s1, 0
	v_readlane_b32 s1, v250, 39
	s_cselect_b32 s6, s1, 0
	s_cselect_b32 s1, 0x80, 0

;     __device__ __forceinline__ void operator()(const f32x4 (&acc)[2][2][4][2], const pg8::Unit& u, int wr, int wc, int fr, int fq) const {
;     ...
;             asm volatile("s_waitcnt lgkmcnt(0)" ::: "memory"); __builtin_amdgcn_s_barrier(); asm volatile("" ::: "memory");
;             const float* gp = g + ((32 * wc + 8 * fq) & (W - 1));
;             g0 = *(const f32x4*)gp; g1 = *(const f32x4*)(gp + 4);
.LBB0_291:
	s_or_b64 exec, exec, s[10:11]
	v_lshl_add_u32 v0, v179, 3, s54
	s_add_i32 s10, s1, -1
	v_and_b32_e32 v0, s10, v0
	s_waitcnt lgkmcnt(0)
	s_barrier
	s_waitcnt lgkmcnt(0)
	v_lshl_add_u64 v[90:91], v[0:1], 2, s[6:7]
	global_load_dwordx4 v[94:97], v[90:91], off
	s_nop 0
	global_load_dwordx4 v[90:93], v[90:91], off offset:16
	v_cndmask_b32_e64 v0, 0, 1, s[8:9]
	v_cmp_ne_u32_e64 s[6:7], 1, v0
	s_andn2_b64 vcc, exec, s[8:9]
	s_cbranch_vccnz .LBB0_294

;     __device__ __forceinline__ void operator()(const f32x4 (&acc)[2][2][4][2], const pg8::Unit& u, int wr, int wc, int fr, int fq) const {
;     ...
;             for (int m = 0; m < 4; ++m) rsv[m] = ssq ? rsqrtf(ssq[row0 + ai * 128 + m * 16] * (1.f / DM) + EPS) : 1.f;
.LBB0_299:
	v_mov_b32_e32 v0, 1.0
	s_and_b64 vcc, exec, s[12:13]
	v_lshl_add_u64 v[158:159], v[154:155], 2, s[44:45]
	v_mov_b32_e32 v160, 1.0
	s_cbranch_vccnz .LBB0_301
	s_waitcnt lgkmcnt(0)
	v_mov_b32_e32 v138, v242
	v_fmamk_f32 v138, v138, 0x3a000000, v205
	v_mul_f32_e32 v139, 0x4b800000, v138
	v_cmp_gt_f32_e32 vcc, s68, v138
	s_nop 1
	v_cndmask_b32_e32 v138, v138, v139, vcc
	v_rsq_f32_e32 v138, v138
	s_nop 0
	v_mul_f32_e32 v139, 0x45800000, v138
	v_cndmask_b32_e32 v160, v138, v139, vcc
.LBB0_301:
	s_and_b64 vcc, exec, s[12:13]
	s_cbranch_vccnz .LBB0_303
	s_waitcnt lgkmcnt(0)
	v_mov_b32_e32 v0, v243
	v_fmamk_f32 v0, v0, 0x3a000000, v205
	v_mul_f32_e32 v138, 0x4b800000, v0
	v_cmp_gt_f32_e32 vcc, s68, v0
	s_nop 1
	v_cndmask_b32_e32 v0, v0, v138, vcc
	v_rsq_f32_e32 v0, v0
	s_nop 0
	v_mul_f32_e32 v138, 0x45800000, v0
	v_cndmask_b32_e32 v0, v0, v138, vcc

; __device__ __forceinline__ unsigned cvt_pk_bf16(float lo, float hi) { unsigned r; asm volatile("v_cvt_pk_bf16_f32 %0, %1, %2" : "=v"(r) : "v"(lo), "v"(hi)); return r; }
; #define LAS __attribute__((address_space(3)))
; __device__ __forceinline__ float gelu_tanh_f(float x) { const float u = 0.7978845608028654f * (x + 0.044715f * x * x * x); return x * fast_rcp(1.f + fast_exp2(-2.f * LOG2E * u)); }
;     __device__ __forceinline__ void operator()(const f32x4 (&acc)[2][2][4][2], const pg8::Unit& u, int wr, int wc, int fr, int fq) const {
;     ...
;             for (int m = 0; m < 4; ++m) { bf16_t* rowp = Z + (size_t)(row0 + ai * 128 + m * 16) * ldc + col0;
;                 const float rs = rsv[m];
; #pragma unroll
;                 for (int bj = 0; bj < 2; ++bj) { float mm = rs;
;                     if (W) { const f32x4 pp = *(const LAS f32x4*)(part + (lrow0 + ai * 128 + m * 16) * 8 + bj * 4);
;                         const float tot = (W == 128) ? ((pp[0] + pp[1]) + (pp[2] + pp[3])) : (wc < 2 ? pp[0] + pp[1] : pp[2] + pp[3]);
;                         mm = rs * rsqrtf(tot * rs * rs * invW + EPS); }
;                     f32x4 v0 = acc[ai][bj][m][0] * mm * g0, v1 = acc[ai][bj][m][1] * mm * g1;
;                     if (act) {
; #pragma unroll
;                         for (int j = 0; j < 4; ++j) { v0[j] = gelu_tanh_f(v0[j]); v1[j] = gelu_tanh_f(v1[j]); } }
;                     u32x4 w; w.x = cvt_pk_bf16(v0[0], v0[1]); w.y = cvt_pk_bf16(v0[2], v0[3]); w.z = cvt_pk_bf16(v1[0], v1[1]); w.w = cvt_pk_bf16(v1[2], v1[3]);
;                     __builtin_nontemporal_store(w, (u32x4*)(rowp + bj * 128)); } } }
.LBB0_315:
	s_lshl_b32 s0, s0, 8
	s_or_b32 s0, s0, s54
	v_lshl_add_u32 v156, v179, 3, s0
	v_mad_u64_u32 v[166:167], s[0:1], v154, s31, 0
	v_mov_b32_e32 v186, v167
	v_ashrrev_i32_e32 v157, 31, v156
	v_mad_u64_u32 v[186:187], s[0:1], v155, s31, v[186:187]
	v_lshl_add_u64 v[156:157], v[156:157], 1, s[42:43]
	v_mov_b32_e32 v167, v186
	v_cvt_pk_bf16_f32 v186, v140, v141
	v_cvt_pk_bf16_f32 v187, v138, v139
	v_cndmask_b32_e64 v138, 0, 1, s[10:11]
	v_lshl_add_u64 v[166:167], v[166:167], 1, v[156:157]
	s_and_b64 vcc, exec, s[6:7]
	v_cmp_ne_u32_e64 s[10:11], 1, v138
	v_cvt_pk_bf16_f32 v188, v168, v169
	v_cvt_pk_bf16_f32 v189, v170, v171
	global_store_dwordx4 v[166:167], v[186:189], off nt
	s_cbranch_vccnz .LBB0_325
	s_add_i32 s0, 0, 0x20000
	v_add_u32_e32 v138, s0, v184
	ds_read_b128 v[138:141], v138 offset:16
	s_and_b64 vcc, exec, s[10:11]
	s_mov_b64 s[0:1], -1
	s_cbranch_vccnz .LBB0_322
	s_andn2_b64 vcc, exec, s[34:35]
	s_cbranch_vccnz .LBB0_319
	s_waitcnt lgkmcnt(0)
	v_add_f32_e32 v155, v140, v141
	s_mov_b64 s[0:1], 0

; __device__ __forceinline__ unsigned cvt_pk_bf16(float lo, float hi) { unsigned r; asm volatile("v_cvt_pk_bf16_f32 %0, %1, %2" : "=v"(r) : "v"(lo), "v"(hi)); return r; }
; #define LAS __attribute__((address_space(3)))
; __device__ __forceinline__ float gelu_tanh_f(float x) { const float u = 0.7978845608028654f * (x + 0.044715f * x * x * x); return x * fast_rcp(1.f + fast_exp2(-2.f * LOG2E * u)); }
;     __device__ __forceinline__ void operator()(const f32x4 (&acc)[2][2][4][2], const pg8::Unit& u, int wr, int wc, int fr, int fq) const {
;     ...
;             for (int m = 0; m < 4; ++m) { bf16_t* rowp = Z + (size_t)(row0 + ai * 128 + m * 16) * ldc + col0;
;                 const float rs = rsv[m];
; #pragma unroll
;                 for (int bj = 0; bj < 2; ++bj) { float mm = rs;
;                     if (W) { const f32x4 pp = *(const LAS f32x4*)(part + (lrow0 + ai * 128 + m * 16) * 8 + bj * 4);
;                         const float tot = (W == 128) ? ((pp[0] + pp[1]) + (pp[2] + pp[3])) : (wc < 2 ? pp[0] + pp[1] : pp[2] + pp[3]);
;                         mm = rs * rsqrtf(tot * rs * rs * invW + EPS); }
;                     f32x4 v0 = acc[ai][bj][m][0] * mm * g0, v1 = acc[ai][bj][m][1] * mm * g1;
;                     if (act) {
; #pragma unroll
;                         for (int j = 0; j < 4; ++j) { v0[j] = gelu_tanh_f(v0[j]); v1[j] = gelu_tanh_f(v1[j]); } }
;                     u32x4 w; w.x = cvt_pk_bf16(v0[0], v0[1]); w.y = cvt_pk_bf16(v0[2], v0[3]); w.z = cvt_pk_bf16(v1[0], v1[1]); w.w = cvt_pk_bf16(v1[2], v1[3]);
;                     __builtin_nontemporal_store(w, (u32x4*)(rowp + bj * 128)); } } }
.LBB0_327:
	v_cvt_pk_bf16_f32 v136, v136, v137
	v_cvt_pk_bf16_f32 v137, v134, v135
	s_and_b64 vcc, exec, s[6:7]
	v_mov_b32_e32 v134, v162
	v_cvt_pk_bf16_f32 v138, v132, v133
	v_cvt_pk_bf16_f32 v139, v130, v131
	global_store_dwordx4 v[166:167], v[136:139], off offset:256 nt
	s_cbranch_vccnz .LBB0_337
	s_add_i32 s0, 0, 0x20000
	v_add_u32_e32 v130, s0, v184
	ds_read_b128 v[130:133], v130 offset:512
	s_and_b64 vcc, exec, s[10:11]
	s_mov_b64 s[0:1], -1
	s_cbranch_vccnz .LBB0_334
	s_andn2_b64 vcc, exec, s[34:35]
	s_cbranch_vccnz .LBB0_331
	s_waitcnt lgkmcnt(0)
	v_add_f32_e32 v134, v132, v133
	s_mov_b64 s[0:1], 0

; __device__ __forceinline__ unsigned cvt_pk_bf16(float lo, float hi) { unsigned r; asm volatile("v_cvt_pk_bf16_f32 %0, %1, %2" : "=v"(r) : "v"(lo), "v"(hi)); return r; }
; #define LAS __attribute__((address_space(3)))
; __device__ __forceinline__ float gelu_tanh_f(float x) { const float u = 0.7978845608028654f * (x + 0.044715f * x * x * x); return x * fast_rcp(1.f + fast_exp2(-2.f * LOG2E * u)); }
;     __device__ __forceinline__ void operator()(const f32x4 (&acc)[2][2][4][2], const pg8::Unit& u, int wr, int wc, int fr, int fq) const {
;     ...
;             for (int m = 0; m < 4; ++m) { bf16_t* rowp = Z + (size_t)(row0 + ai * 128 + m * 16) * ldc + col0;
;                 const float rs = rsv[m];
; #pragma unroll
;                 for (int bj = 0; bj < 2; ++bj) { float mm = rs;
;                     if (W) { const f32x4 pp = *(const LAS f32x4*)(part + (lrow0 + ai * 128 + m * 16) * 8 + bj * 4);
;                         const float tot = (W == 128) ? ((pp[0] + pp[1]) + (pp[2] + pp[3])) : (wc < 2 ? pp[0] + pp[1] : pp[2] + pp[3]);
;                         mm = rs * rsqrtf(tot * rs * rs * invW + EPS); }
;                     f32x4 v0 = acc[ai][bj][m][0] * mm * g0, v1 = acc[ai][bj][m][1] * mm * g1;
;                     if (act) {
; #pragma unroll
;                         for (int j = 0; j < 4; ++j) { v0[j] = gelu_tanh_f(v0[j]); v1[j] = gelu_tanh_f(v1[j]); } }
;                     u32x4 w; w.x = cvt_pk_bf16(v0[0], v0[1]); w.y = cvt_pk_bf16(v0[2], v0[3]); w.z = cvt_pk_bf16(v1[0], v1[1]); w.w = cvt_pk_bf16(v1[2], v1[3]);
;                     __builtin_nontemporal_store(w, (u32x4*)(rowp + bj * 128)); } } }
.LBB0_339:
	v_add_u32_e32 v134, 16, v154
	v_mad_i64_i32 v[134:135], s[0:1], v134, s31, 0
	v_lshl_add_u64 v[134:135], v[134:135], 1, v[156:157]
	s_and_b64 vcc, exec, s[6:7]
	v_cvt_pk_bf16_f32 v166, v132, v133
	v_cvt_pk_bf16_f32 v167, v130, v131
	v_cvt_pk_bf16_f32 v168, v138, v139
	v_cvt_pk_bf16_f32 v169, v136, v137
	global_store_dwordx4 v[134:135], v[166:169], off nt
	s_cbranch_vccnz .LBB0_349
	s_add_i32 s0, 0, 0x20000
	v_add_u32_e32 v130, s0, v184
	ds_read_b128 v[130:133], v130 offset:528
	s_and_b64 vcc, exec, s[10:11]
	s_mov_b64 s[0:1], -1
	s_cbranch_vccnz .LBB0_346
	s_andn2_b64 vcc, exec, s[34:35]
	s_cbranch_vccnz .LBB0_343
	s_waitcnt lgkmcnt(0)
	v_add_f32_e32 v136, v132, v133
	s_mov_b64 s[0:1], 0

; __device__ __forceinline__ unsigned cvt_pk_bf16(float lo, float hi) { unsigned r; asm volatile("v_cvt_pk_bf16_f32 %0, %1, %2" : "=v"(r) : "v"(lo), "v"(hi)); return r; }
; #define LAS __attribute__((address_space(3)))
; __device__ __forceinline__ float gelu_tanh_f(float x) { const float u = 0.7978845608028654f * (x + 0.044715f * x * x * x); return x * fast_rcp(1.f + fast_exp2(-2.f * LOG2E * u)); }
;     __device__ __forceinline__ void operator()(const f32x4 (&acc)[2][2][4][2], const pg8::Unit& u, int wr, int wc, int fr, int fq) const {
;     ...
;             for (int m = 0; m < 4; ++m) { bf16_t* rowp = Z + (size_t)(row0 + ai * 128 + m * 16) * ldc + col0;
;                 const float rs = rsv[m];
; #pragma unroll
;                 for (int bj = 0; bj < 2; ++bj) { float mm = rs;
;                     if (W) { const f32x4 pp = *(const LAS f32x4*)(part + (lrow0 + ai * 128 + m * 16) * 8 + bj * 4);
;                         const float tot = (W == 128) ? ((pp[0] + pp[1]) + (pp[2] + pp[3])) : (wc < 2 ? pp[0] + pp[1] : pp[2] + pp[3]);
;                         mm = rs * rsqrtf(tot * rs * rs * invW + EPS); }
;                     f32x4 v0 = acc[ai][bj][m][0] * mm * g0, v1 = acc[ai][bj][m][1] * mm * g1;
;                     if (act) {
; #pragma unroll
;                         for (int j = 0; j < 4; ++j) { v0[j] = gelu_tanh_f(v0[j]); v1[j] = gelu_tanh_f(v1[j]); } }
;                     u32x4 w; w.x = cvt_pk_bf16(v0[0], v0[1]); w.y = cvt_pk_bf16(v0[2], v0[3]); w.z = cvt_pk_bf16(v1[0], v1[1]); w.w = cvt_pk_bf16(v1[2], v1[3]);
;                     __builtin_nontemporal_store(w, (u32x4*)(rowp + bj * 128)); } } }
.LBB0_351:
	v_cvt_pk_bf16_f32 v128, v128, v129
	v_cvt_pk_bf16_f32 v129, v126, v127
	s_and_b64 vcc, exec, s[6:7]
	v_mov_b32_e32 v126, v160
	v_cvt_pk_bf16_f32 v130, v124, v125
	v_cvt_pk_bf16_f32 v131, v122, v123
	global_store_dwordx4 v[134:135], v[128:131], off offset:256 nt
	s_cbranch_vccnz .LBB0_361
	s_add_i32 s0, 0, 0x20000
	v_add_u32_e32 v122, s0, v184
	ds_read_b128 v[122:125], v122 offset:1024
	s_and_b64 vcc, exec, s[10:11]
	s_mov_b64 s[0:1], -1
	s_cbranch_vccnz .LBB0_358
	s_andn2_b64 vcc, exec, s[34:35]
	s_cbranch_vccnz .LBB0_355
	s_waitcnt lgkmcnt(0)
	v_add_f32_e32 v126, v124, v125
	s_mov_b64 s[0:1], 0

; __device__ __forceinline__ unsigned cvt_pk_bf16(float lo, float hi) { unsigned r; asm volatile("v_cvt_pk_bf16_f32 %0, %1, %2" : "=v"(r) : "v"(lo), "v"(hi)); return r; }
; #define LAS __attribute__((address_space(3)))
; __device__ __forceinline__ float gelu_tanh_f(float x) { const float u = 0.7978845608028654f * (x + 0.044715f * x * x * x); return x * fast_rcp(1.f + fast_exp2(-2.f * LOG2E * u)); }
;     __device__ __forceinline__ void operator()(const f32x4 (&acc)[2][2][4][2], const pg8::Unit& u, int wr, int wc, int fr, int fq) const {
;     ...
;             for (int m = 0; m < 4; ++m) { bf16_t* rowp = Z + (size_t)(row0 + ai * 128 + m * 16) * ldc + col0;
;                 const float rs = rsv[m];
; #pragma unroll
;                 for (int bj = 0; bj < 2; ++bj) { float mm = rs;
;                     if (W) { const f32x4 pp = *(const LAS f32x4*)(part + (lrow0 + ai * 128 + m * 16) * 8 + bj * 4);
;                         const float tot = (W == 128) ? ((pp[0] + pp[1]) + (pp[2] + pp[3])) : (wc < 2 ? pp[0] + pp[1] : pp[2] + pp[3]);
;                         mm = rs * rsqrtf(tot * rs * rs * invW + EPS); }
;                     f32x4 v0 = acc[ai][bj][m][0] * mm * g0, v1 = acc[ai][bj][m][1] * mm * g1;
;                     if (act) {
; #pragma unroll
;                         for (int j = 0; j < 4; ++j) { v0[j] = gelu_tanh_f(v0[j]); v1[j] = gelu_tanh_f(v1[j]); } }
;                     u32x4 w; w.x = cvt_pk_bf16(v0[0], v0[1]); w.y = cvt_pk_bf16(v0[2], v0[3]); w.z = cvt_pk_bf16(v1[0], v1[1]); w.w = cvt_pk_bf16(v1[2], v1[3]);
;                     __builtin_nontemporal_store(w, (u32x4*)(rowp + bj * 128)); } } }
.LBB0_363:
	v_add_u32_e32 v126, 32, v154
	v_mad_i64_i32 v[126:127], s[0:1], v126, s31, 0
	v_lshl_add_u64 v[126:127], v[126:127], 1, v[156:157]
	s_and_b64 vcc, exec, s[6:7]
	v_cvt_pk_bf16_f32 v132, v124, v125
	v_cvt_pk_bf16_f32 v133, v122, v123
	v_cvt_pk_bf16_f32 v134, v130, v131
	v_cvt_pk_bf16_f32 v135, v128, v129
	global_store_dwordx4 v[126:127], v[132:135], off nt
	s_cbranch_vccnz .LBB0_373
	s_add_i32 s0, 0, 0x20000
	v_add_u32_e32 v122, s0, v184
	ds_read_b128 v[122:125], v122 offset:1040
	s_and_b64 vcc, exec, s[10:11]
	s_mov_b64 s[0:1], -1
	s_cbranch_vccnz .LBB0_370
	s_andn2_b64 vcc, exec, s[34:35]
	s_cbranch_vccnz .LBB0_367
	s_waitcnt lgkmcnt(0)
	v_add_f32_e32 v128, v124, v125
	s_mov_b64 s[0:1], 0

; __device__ __forceinline__ unsigned cvt_pk_bf16(float lo, float hi) { unsigned r; asm volatile("v_cvt_pk_bf16_f32 %0, %1, %2" : "=v"(r) : "v"(lo), "v"(hi)); return r; }
; #define LAS __attribute__((address_space(3)))
; __device__ __forceinline__ float gelu_tanh_f(float x) { const float u = 0.7978845608028654f * (x + 0.044715f * x * x * x); return x * fast_rcp(1.f + fast_exp2(-2.f * LOG2E * u)); }
;     __device__ __forceinline__ void operator()(const f32x4 (&acc)[2][2][4][2], const pg8::Unit& u, int wr, int wc, int fr, int fq) const {
;     ...
;             for (int m = 0; m < 4; ++m) { bf16_t* rowp = Z + (size_t)(row0 + ai * 128 + m * 16) * ldc + col0;
;                 const float rs = rsv[m];
; #pragma unroll
;                 for (int bj = 0; bj < 2; ++bj) { float mm = rs;
;                     if (W) { const f32x4 pp = *(const LAS f32x4*)(part + (lrow0 + ai * 128 + m * 16) * 8 + bj * 4);
;                         const float tot = (W == 128) ? ((pp[0] + pp[1]) + (pp[2] + pp[3])) : (wc < 2 ? pp[0] + pp[1] : pp[2] + pp[3]);
;                         mm = rs * rsqrtf(tot * rs * rs * invW + EPS); }
;                     f32x4 v0 = acc[ai][bj][m][0] * mm * g0, v1 = acc[ai][bj][m][1] * mm * g1;
;                     if (act) {
; #pragma unroll
;                         for (int j = 0; j < 4; ++j) { v0[j] = gelu_tanh_f(v0[j]); v1[j] = gelu_tanh_f(v1[j]); } }
;                     u32x4 w; w.x = cvt_pk_bf16(v0[0], v0[1]); w.y = cvt_pk_bf16(v0[2], v0[3]); w.z = cvt_pk_bf16(v1[0], v1[1]); w.w = cvt_pk_bf16(v1[2], v1[3]);
;                     __builtin_nontemporal_store(w, (u32x4*)(rowp + bj * 128)); } } }
.LBB0_375:
	v_cvt_pk_bf16_f32 v120, v120, v121
	v_cvt_pk_bf16_f32 v121, v118, v119
	s_and_b64 vcc, exec, s[6:7]
	v_mov_b32_e32 v118, v0
	v_cvt_pk_bf16_f32 v122, v116, v117
	v_cvt_pk_bf16_f32 v123, v114, v115
	global_store_dwordx4 v[126:127], v[120:123], off offset:256 nt
	s_cbranch_vccnz .LBB0_385
	s_add_i32 s0, 0, 0x20000
	v_add_u32_e32 v114, s0, v184
	ds_read_b128 v[114:117], v114 offset:1536
	s_and_b64 vcc, exec, s[10:11]
	s_mov_b64 s[0:1], -1
	s_cbranch_vccnz .LBB0_382
	s_andn2_b64 vcc, exec, s[34:35]
	s_cbranch_vccnz .LBB0_379
	s_waitcnt lgkmcnt(0)
	v_add_f32_e32 v118, v116, v117
	s_mov_b64 s[0:1], 0

; __device__ __forceinline__ unsigned cvt_pk_bf16(float lo, float hi) { unsigned r; asm volatile("v_cvt_pk_bf16_f32 %0, %1, %2" : "=v"(r) : "v"(lo), "v"(hi)); return r; }
; #define LAS __attribute__((address_space(3)))
; __device__ __forceinline__ float gelu_tanh_f(float x) { const float u = 0.7978845608028654f * (x + 0.044715f * x * x * x); return x * fast_rcp(1.f + fast_exp2(-2.f * LOG2E * u)); }
;     __device__ __forceinline__ void operator()(const f32x4 (&acc)[2][2][4][2], const pg8::Unit& u, int wr, int wc, int fr, int fq) const {
;     ...
;             for (int m = 0; m < 4; ++m) { bf16_t* rowp = Z + (size_t)(row0 + ai * 128 + m * 16) * ldc + col0;
;                 const float rs = rsv[m];
; #pragma unroll
;                 for (int bj = 0; bj < 2; ++bj) { float mm = rs;
;                     if (W) { const f32x4 pp = *(const LAS f32x4*)(part + (lrow0 + ai * 128 + m * 16) * 8 + bj * 4);
;                         const float tot = (W == 128) ? ((pp[0] + pp[1]) + (pp[2] + pp[3])) : (wc < 2 ? pp[0] + pp[1] : pp[2] + pp[3]);
;                         mm = rs * rsqrtf(tot * rs * rs * invW + EPS); }
;                     f32x4 v0 = acc[ai][bj][m][0] * mm * g0, v1 = acc[ai][bj][m][1] * mm * g1;
;                     if (act) {
; #pragma unroll
;                         for (int j = 0; j < 4; ++j) { v0[j] = gelu_tanh_f(v0[j]); v1[j] = gelu_tanh_f(v1[j]); } }
;                     u32x4 w; w.x = cvt_pk_bf16(v0[0], v0[1]); w.y = cvt_pk_bf16(v0[2], v0[3]); w.z = cvt_pk_bf16(v1[0], v1[1]); w.w = cvt_pk_bf16(v1[2], v1[3]);
;                     __builtin_nontemporal_store(w, (u32x4*)(rowp + bj * 128)); } } }
.LBB0_387:
	v_add_u32_e32 v118, 48, v154
	v_mad_i64_i32 v[118:119], s[0:1], v118, s31, 0
	v_lshl_add_u64 v[118:119], v[118:119], 1, v[156:157]
	s_and_b64 vcc, exec, s[6:7]
	v_cvt_pk_bf16_f32 v124, v116, v117
	v_cvt_pk_bf16_f32 v125, v114, v115
	v_cvt_pk_bf16_f32 v126, v122, v123
	v_cvt_pk_bf16_f32 v127, v120, v121
	global_store_dwordx4 v[118:119], v[124:127], off nt
	s_cbranch_vccnz .LBB0_397
	s_add_i32 s0, 0, 0x20000
	v_add_u32_e32 v114, s0, v184
	ds_read_b128 v[114:117], v114 offset:1552
	s_and_b64 vcc, exec, s[10:11]
	s_mov_b64 s[0:1], -1
	s_cbranch_vccnz .LBB0_394
	s_andn2_b64 vcc, exec, s[34:35]
	s_cbranch_vccnz .LBB0_391
	s_waitcnt lgkmcnt(0)
	v_add_f32_e32 v120, v116, v117
	s_mov_b64 s[0:1], 0

; __device__ __forceinline__ unsigned cvt_pk_bf16(float lo, float hi) { unsigned r; asm volatile("v_cvt_pk_bf16_f32 %0, %1, %2" : "=v"(r) : "v"(lo), "v"(hi)); return r; }
; #define LAS __attribute__((address_space(3)))
; __device__ __forceinline__ float gelu_tanh_f(float x) { const float u = 0.7978845608028654f * (x + 0.044715f * x * x * x); return x * fast_rcp(1.f + fast_exp2(-2.f * LOG2E * u)); }
;     __device__ __forceinline__ void operator()(const f32x4 (&acc)[2][2][4][2], const pg8::Unit& u, int wr, int wc, int fr, int fq) const {
;     ...
;             for (int m = 0; m < 4; ++m) rsv[m] = ssq ? rsqrtf(ssq[row0 + ai * 128 + m * 16] * (1.f / DM) + EPS) : 1.f;
; #pragma unroll
;             for (int m = 0; m < 4; ++m) { bf16_t* rowp = Z + (size_t)(row0 + ai * 128 + m * 16) * ldc + col0;
;                 const float rs = rsv[m];
; #pragma unroll
;                 for (int bj = 0; bj < 2; ++bj) { float mm = rs;
;                     if (W) { const f32x4 pp = *(const LAS f32x4*)(part + (lrow0 + ai * 128 + m * 16) * 8 + bj * 4);
;                         const float tot = (W == 128) ? ((pp[0] + pp[1]) + (pp[2] + pp[3])) : (wc < 2 ? pp[0] + pp[1] : pp[2] + pp[3]);
;                         mm = rs * rsqrtf(tot * rs * rs * invW + EPS); }
;                     f32x4 v0 = acc[ai][bj][m][0] * mm * g0, v1 = acc[ai][bj][m][1] * mm * g1;
;                     if (act) {
; #pragma unroll
;                         for (int j = 0; j < 4; ++j) { v0[j] = gelu_tanh_f(v0[j]); v1[j] = gelu_tanh_f(v1[j]); } }
;                     u32x4 w; w.x = cvt_pk_bf16(v0[0], v0[1]); w.y = cvt_pk_bf16(v0[2], v0[3]); w.z = cvt_pk_bf16(v1[0], v1[1]); w.w = cvt_pk_bf16(v1[2], v1[3]);
;                     __builtin_nontemporal_store(w, (u32x4*)(rowp + bj * 128)); } } }
.LBB0_399:
	v_cvt_pk_bf16_f32 v112, v112, v113
	v_cvt_pk_bf16_f32 v113, v110, v111
	v_cvt_pk_bf16_f32 v114, v108, v109
	s_nop 0
	v_cvt_pk_bf16_f32 v115, v106, v107
	global_store_dwordx4 v[118:119], v[112:115], off offset:256 nt
	s_and_b64 vcc, exec, s[12:13]
	s_nop 0
	v_mov_b32_e32 v112, 1.0
	v_mov_b32_e32 v114, 1.0
	s_cbranch_vccz .LBB0_406
	s_and_b64 vcc, exec, s[12:13]
	s_cbranch_vccz .LBB0_407

;     __device__ __forceinline__ void operator()(const f32x4 (&acc)[2][2][4][2], const pg8::Unit& u, int wr, int wc, int fr, int fq) const {
;     ...
;             for (int m = 0; m < 4; ++m) rsv[m] = ssq ? rsqrtf(ssq[row0 + ai * 128 + m * 16] * (1.f / DM) + EPS) : 1.f;
.LBB0_404:
	v_ashrrev_i32_e32 v155, 31, v154
	v_lshl_add_u64 v[138:139], v[154:155], 2, s[44:45]
	s_waitcnt vmcnt(0) lgkmcnt(0)
	v_mov_b32_e32 v0, v240
	v_fmamk_f32 v0, v0, 0x3a000000, v205
	v_mul_f32_e32 v138, 0x4b800000, v0
	v_cmp_gt_f32_e32 vcc, s68, v0
	s_nop 1
	v_cndmask_b32_e32 v0, v0, v138, vcc
	v_rsq_f32_e32 v0, v0
	s_nop 0
	v_mul_f32_e32 v138, 0x45800000, v0
	v_cndmask_b32_e32 v164, v0, v138, vcc
	s_mov_b64 s[8:9], -1
	s_and_b64 vcc, exec, s[40:41]
	s_cbranch_vccz .LBB0_297
.LBB0_405:
	v_ashrrev_i32_e32 v155, 31, v154
	v_lshl_add_u64 v[138:139], v[154:155], 2, s[44:45]
	s_waitcnt vmcnt(0) lgkmcnt(0)
	v_mov_b32_e32 v0, v241
	v_fmamk_f32 v0, v0, 0x3a000000, v205
	v_mul_f32_e32 v138, 0x4b800000, v0
	v_cmp_gt_f32_e32 vcc, s68, v0
	s_nop 1
	v_cndmask_b32_e32 v0, v0, v138, vcc
	v_rsq_f32_e32 v0, v0
	s_nop 0
	v_mul_f32_e32 v138, 0x45800000, v0
	v_cndmask_b32_e32 v162, v0, v138, vcc
	s_cbranch_execz .LBB0_298
	s_branch .LBB0_299
.LBB0_406:
	s_waitcnt lgkmcnt(0)
	v_mov_b32_e32 v0, v244
	v_fmamk_f32 v0, v0, 0x3a000000, v205
	v_mul_f32_e32 v106, 0x4b800000, v0
	v_cmp_gt_f32_e32 vcc, s68, v0
	s_nop 1
	v_cndmask_b32_e32 v0, v0, v106, vcc
	v_rsq_f32_e32 v0, v0
	s_nop 0
	v_mul_f32_e32 v106, 0x45800000, v0
	v_cndmask_b32_e32 v114, v0, v106, vcc
	s_and_b64 vcc, exec, s[12:13]
	s_cbranch_vccnz .LBB0_401
.LBB0_407:
	s_waitcnt lgkmcnt(0)
	v_mov_b32_e32 v0, v245
	v_fmamk_f32 v0, v0, 0x3a000000, v205
	v_mul_f32_e32 v106, 0x4b800000, v0
	v_cmp_gt_f32_e32 vcc, s68, v0
	s_nop 1
	v_cndmask_b32_e32 v0, v0, v106, vcc
	v_rsq_f32_e32 v0, v0
	s_nop 0
	v_mul_f32_e32 v106, 0x45800000, v0
	v_cndmask_b32_e32 v112, v0, v106, vcc
	v_mov_b32_e32 v0, 1.0
	s_and_b64 vcc, exec, s[12:13]
	v_mov_b32_e32 v110, 1.0
	s_cbranch_vccnz .LBB0_402
.LBB0_408:
	s_waitcnt lgkmcnt(0)
	v_mov_b32_e32 v106, v246
	v_fmamk_f32 v106, v106, 0x3a000000, v205
	v_mul_f32_e32 v107, 0x4b800000, v106
	v_cmp_gt_f32_e32 vcc, s68, v106
	s_nop 1
	v_cndmask_b32_e32 v106, v106, v107, vcc
	v_rsq_f32_e32 v106, v106
	s_nop 0
	v_mul_f32_e32 v107, 0x45800000, v106
	v_cndmask_b32_e32 v110, v106, v107, vcc
	s_and_b64 vcc, exec, s[12:13]
	s_cbranch_vccnz .LBB0_403
.LBB0_409:
	s_waitcnt lgkmcnt(0)
	v_mov_b32_e32 v0, v247
	v_fmamk_f32 v0, v0, 0x3a000000, v205
	v_mul_f32_e32 v106, 0x4b800000, v0
	v_cmp_gt_f32_e32 vcc, s68, v0
	s_nop 1
	v_cndmask_b32_e32 v0, v0, v106, vcc
	v_rsq_f32_e32 v0, v0
	s_nop 0
	v_mul_f32_e32 v106, 0x45800000, v0
	v_cndmask_b32_e32 v0, v0, v106, vcc
	s_and_b64 vcc, exec, s[6:7]
	v_mov_b32_e32 v116, v114
	s_cbranch_vccnz .LBB0_419

; __device__ __forceinline__ unsigned cvt_pk_bf16(float lo, float hi) { unsigned r; asm volatile("v_cvt_pk_bf16_f32 %0, %1, %2" : "=v"(r) : "v"(lo), "v"(hi)); return r; }
; #define LAS __attribute__((address_space(3)))
; __device__ __forceinline__ float gelu_tanh_f(float x) { const float u = 0.7978845608028654f * (x + 0.044715f * x * x * x); return x * fast_rcp(1.f + fast_exp2(-2.f * LOG2E * u)); }
;     __device__ __forceinline__ void operator()(const f32x4 (&acc)[2][2][4][2], const pg8::Unit& u, int wr, int wc, int fr, int fq) const {
;     ...
;             for (int m = 0; m < 4; ++m) { bf16_t* rowp = Z + (size_t)(row0 + ai * 128 + m * 16) * ldc + col0;
;                 const float rs = rsv[m];
; #pragma unroll
;                 for (int bj = 0; bj < 2; ++bj) { float mm = rs;
;                     if (W) { const f32x4 pp = *(const LAS f32x4*)(part + (lrow0 + ai * 128 + m * 16) * 8 + bj * 4);
;                         const float tot = (W == 128) ? ((pp[0] + pp[1]) + (pp[2] + pp[3])) : (wc < 2 ? pp[0] + pp[1] : pp[2] + pp[3]);
;                         mm = rs * rsqrtf(tot * rs * rs * invW + EPS); }
;                     f32x4 v0 = acc[ai][bj][m][0] * mm * g0, v1 = acc[ai][bj][m][1] * mm * g1;
;                     if (act) {
; #pragma unroll
;                         for (int j = 0; j < 4; ++j) { v0[j] = gelu_tanh_f(v0[j]); v1[j] = gelu_tanh_f(v1[j]); } }
;                     u32x4 w; w.x = cvt_pk_bf16(v0[0], v0[1]); w.y = cvt_pk_bf16(v0[2], v0[3]); w.z = cvt_pk_bf16(v1[0], v1[1]); w.w = cvt_pk_bf16(v1[2], v1[3]);
;                     __builtin_nontemporal_store(w, (u32x4*)(rowp + bj * 128)); } } }
.LBB0_421:
	v_add_u32_e32 v111, 0x80, v154
	v_mad_i64_i32 v[116:117], s[0:1], v111, s31, 0
	v_lshl_add_u64 v[116:117], v[116:117], 1, v[156:157]
	s_and_b64 vcc, exec, s[6:7]
	v_cvt_pk_bf16_f32 v122, v108, v109
	v_cvt_pk_bf16_f32 v123, v106, v107
	v_cvt_pk_bf16_f32 v124, v120, v121
	v_cvt_pk_bf16_f32 v125, v118, v119
	global_store_dwordx4 v[116:117], v[122:125], off nt
	s_cbranch_vccnz .LBB0_431
	s_add_i32 s0, 0, 0x20000
	v_add_u32_e32 v106, s0, v184
	ds_read_b128 v[106:109], v106 offset:4112
	s_and_b64 vcc, exec, s[10:11]
	s_mov_b64 s[0:1], -1
	s_cbranch_vccnz .LBB0_428
	s_andn2_b64 vcc, exec, s[34:35]
	s_cbranch_vccnz .LBB0_425
	s_waitcnt lgkmcnt(0)
	v_add_f32_e32 v111, v108, v109
	s_mov_b64 s[0:1], 0

; __device__ __forceinline__ unsigned cvt_pk_bf16(float lo, float hi) { unsigned r; asm volatile("v_cvt_pk_bf16_f32 %0, %1, %2" : "=v"(r) : "v"(lo), "v"(hi)); return r; }
; #define LAS __attribute__((address_space(3)))
; __device__ __forceinline__ float gelu_tanh_f(float x) { const float u = 0.7978845608028654f * (x + 0.044715f * x * x * x); return x * fast_rcp(1.f + fast_exp2(-2.f * LOG2E * u)); }
;     __device__ __forceinline__ void operator()(const f32x4 (&acc)[2][2][4][2], const pg8::Unit& u, int wr, int wc, int fr, int fq) const {
;     ...
;             for (int m = 0; m < 4; ++m) { bf16_t* rowp = Z + (size_t)(row0 + ai * 128 + m * 16) * ldc + col0;
;                 const float rs = rsv[m];
; #pragma unroll
;                 for (int bj = 0; bj < 2; ++bj) { float mm = rs;
;                     if (W) { const f32x4 pp = *(const LAS f32x4*)(part + (lrow0 + ai * 128 + m * 16) * 8 + bj * 4);
;                         const float tot = (W == 128) ? ((pp[0] + pp[1]) + (pp[2] + pp[3])) : (wc < 2 ? pp[0] + pp[1] : pp[2] + pp[3]);
;                         mm = rs * rsqrtf(tot * rs * rs * invW + EPS); }
;                     f32x4 v0 = acc[ai][bj][m][0] * mm * g0, v1 = acc[ai][bj][m][1] * mm * g1;
;                     if (act) {
; #pragma unroll
;                         for (int j = 0; j < 4; ++j) { v0[j] = gelu_tanh_f(v0[j]); v1[j] = gelu_tanh_f(v1[j]); } }
;                     u32x4 w; w.x = cvt_pk_bf16(v0[0], v0[1]); w.y = cvt_pk_bf16(v0[2], v0[3]); w.z = cvt_pk_bf16(v1[0], v1[1]); w.w = cvt_pk_bf16(v1[2], v1[3]);
;                     __builtin_nontemporal_store(w, (u32x4*)(rowp + bj * 128)); } } }
.LBB0_433:
	v_cvt_pk_bf16_f32 v104, v104, v105
	v_cvt_pk_bf16_f32 v105, v102, v103
	s_and_b64 vcc, exec, s[6:7]
	v_mov_b32_e32 v102, v112
	v_cvt_pk_bf16_f32 v106, v100, v101
	v_cvt_pk_bf16_f32 v107, v98, v99
	global_store_dwordx4 v[116:117], v[104:107], off offset:256 nt
	s_cbranch_vccnz .LBB0_443
	s_add_i32 s0, 0, 0x20000
	v_add_u32_e32 v98, s0, v184
	ds_read_b128 v[98:101], v98 offset:4608
	s_and_b64 vcc, exec, s[10:11]
	s_mov_b64 s[0:1], -1
	s_cbranch_vccnz .LBB0_440
	s_andn2_b64 vcc, exec, s[34:35]
	s_cbranch_vccnz .LBB0_437
	s_waitcnt lgkmcnt(0)
	v_add_f32_e32 v102, v100, v101
	s_mov_b64 s[0:1], 0

; __device__ __forceinline__ unsigned cvt_pk_bf16(float lo, float hi) { unsigned r; asm volatile("v_cvt_pk_bf16_f32 %0, %1, %2" : "=v"(r) : "v"(lo), "v"(hi)); return r; }
; #define LAS __attribute__((address_space(3)))
; __device__ __forceinline__ float gelu_tanh_f(float x) { const float u = 0.7978845608028654f * (x + 0.044715f * x * x * x); return x * fast_rcp(1.f + fast_exp2(-2.f * LOG2E * u)); }
;     __device__ __forceinline__ void operator()(const f32x4 (&acc)[2][2][4][2], const pg8::Unit& u, int wr, int wc, int fr, int fq) const {
;     ...
;             for (int m = 0; m < 4; ++m) { bf16_t* rowp = Z + (size_t)(row0 + ai * 128 + m * 16) * ldc + col0;
;                 const float rs = rsv[m];
; #pragma unroll
;                 for (int bj = 0; bj < 2; ++bj) { float mm = rs;
;                     if (W) { const f32x4 pp = *(const LAS f32x4*)(part + (lrow0 + ai * 128 + m * 16) * 8 + bj * 4);
;                         const float tot = (W == 128) ? ((pp[0] + pp[1]) + (pp[2] + pp[3])) : (wc < 2 ? pp[0] + pp[1] : pp[2] + pp[3]);
;                         mm = rs * rsqrtf(tot * rs * rs * invW + EPS); }
;                     f32x4 v0 = acc[ai][bj][m][0] * mm * g0, v1 = acc[ai][bj][m][1] * mm * g1;
;                     if (act) {
; #pragma unroll
;                         for (int j = 0; j < 4; ++j) { v0[j] = gelu_tanh_f(v0[j]); v1[j] = gelu_tanh_f(v1[j]); } }
;                     u32x4 w; w.x = cvt_pk_bf16(v0[0], v0[1]); w.y = cvt_pk_bf16(v0[2], v0[3]); w.z = cvt_pk_bf16(v1[0], v1[1]); w.w = cvt_pk_bf16(v1[2], v1[3]);
;                     __builtin_nontemporal_store(w, (u32x4*)(rowp + bj * 128)); } } }
.LBB0_445:
	v_add_u32_e32 v102, 0x90, v154
	v_mad_i64_i32 v[102:103], s[0:1], v102, s31, 0
	v_lshl_add_u64 v[102:103], v[102:103], 1, v[156:157]
	s_and_b64 vcc, exec, s[6:7]
	v_cvt_pk_bf16_f32 v114, v100, v101
	v_cvt_pk_bf16_f32 v115, v98, v99
	v_cvt_pk_bf16_f32 v116, v106, v107
	v_cvt_pk_bf16_f32 v117, v104, v105
	global_store_dwordx4 v[102:103], v[114:117], off nt
	s_cbranch_vccnz .LBB0_455
	s_add_i32 s0, 0, 0x20000
	v_add_u32_e32 v98, s0, v184
	ds_read_b128 v[98:101], v98 offset:4624
	s_and_b64 vcc, exec, s[10:11]
	s_mov_b64 s[0:1], -1
	s_cbranch_vccnz .LBB0_452
	s_andn2_b64 vcc, exec, s[34:35]
	s_cbranch_vccnz .LBB0_449
	s_waitcnt lgkmcnt(0)
	v_add_f32_e32 v104, v100, v101
	s_mov_b64 s[0:1], 0

; __device__ __forceinline__ unsigned cvt_pk_bf16(float lo, float hi) { unsigned r; asm volatile("v_cvt_pk_bf16_f32 %0, %1, %2" : "=v"(r) : "v"(lo), "v"(hi)); return r; }
; #define LAS __attribute__((address_space(3)))
; __device__ __forceinline__ float gelu_tanh_f(float x) { const float u = 0.7978845608028654f * (x + 0.044715f * x * x * x); return x * fast_rcp(1.f + fast_exp2(-2.f * LOG2E * u)); }
;     __device__ __forceinline__ void operator()(const f32x4 (&acc)[2][2][4][2], const pg8::Unit& u, int wr, int wc, int fr, int fq) const {
;     ...
;             for (int m = 0; m < 4; ++m) { bf16_t* rowp = Z + (size_t)(row0 + ai * 128 + m * 16) * ldc + col0;
;                 const float rs = rsv[m];
; #pragma unroll
;                 for (int bj = 0; bj < 2; ++bj) { float mm = rs;
;                     if (W) { const f32x4 pp = *(const LAS f32x4*)(part + (lrow0 + ai * 128 + m * 16) * 8 + bj * 4);
;                         const float tot = (W == 128) ? ((pp[0] + pp[1]) + (pp[2] + pp[3])) : (wc < 2 ? pp[0] + pp[1] : pp[2] + pp[3]);
;                         mm = rs * rsqrtf(tot * rs * rs * invW + EPS); }
;                     f32x4 v0 = acc[ai][bj][m][0] * mm * g0, v1 = acc[ai][bj][m][1] * mm * g1;
;                     if (act) {
; #pragma unroll
;                         for (int j = 0; j < 4; ++j) { v0[j] = gelu_tanh_f(v0[j]); v1[j] = gelu_tanh_f(v1[j]); } }
;                     u32x4 w; w.x = cvt_pk_bf16(v0[0], v0[1]); w.y = cvt_pk_bf16(v0[2], v0[3]); w.z = cvt_pk_bf16(v1[0], v1[1]); w.w = cvt_pk_bf16(v1[2], v1[3]);
;                     __builtin_nontemporal_store(w, (u32x4*)(rowp + bj * 128)); } } }
.LBB0_457:
	v_cvt_pk_bf16_f32 v98, v88, v89
	v_cvt_pk_bf16_f32 v99, v86, v87
	s_and_b64 vcc, exec, s[6:7]
	v_mov_b32_e32 v86, v110
	v_cvt_pk_bf16_f32 v100, v84, v85
	v_cvt_pk_bf16_f32 v101, v82, v83
	global_store_dwordx4 v[102:103], v[98:101], off offset:256 nt
	s_cbranch_vccnz .LBB0_467
	s_add_i32 s0, 0, 0x20000
	v_add_u32_e32 v82, s0, v184
	ds_read_b128 v[82:85], v82 offset:5120
	s_and_b64 vcc, exec, s[10:11]
	s_mov_b64 s[0:1], -1
	s_cbranch_vccnz .LBB0_464
	s_andn2_b64 vcc, exec, s[34:35]
	s_cbranch_vccnz .LBB0_461
	s_waitcnt lgkmcnt(0)
	v_add_f32_e32 v86, v84, v85
	s_mov_b64 s[0:1], 0

; __device__ __forceinline__ unsigned cvt_pk_bf16(float lo, float hi) { unsigned r; asm volatile("v_cvt_pk_bf16_f32 %0, %1, %2" : "=v"(r) : "v"(lo), "v"(hi)); return r; }
; #define LAS __attribute__((address_space(3)))
; __device__ __forceinline__ float gelu_tanh_f(float x) { const float u = 0.7978845608028654f * (x + 0.044715f * x * x * x); return x * fast_rcp(1.f + fast_exp2(-2.f * LOG2E * u)); }
;     __device__ __forceinline__ void operator()(const f32x4 (&acc)[2][2][4][2], const pg8::Unit& u, int wr, int wc, int fr, int fq) const {
;     ...
;             for (int m = 0; m < 4; ++m) { bf16_t* rowp = Z + (size_t)(row0 + ai * 128 + m * 16) * ldc + col0;
;                 const float rs = rsv[m];
; #pragma unroll
;                 for (int bj = 0; bj < 2; ++bj) { float mm = rs;
;                     if (W) { const f32x4 pp = *(const LAS f32x4*)(part + (lrow0 + ai * 128 + m * 16) * 8 + bj * 4);
;                         const float tot = (W == 128) ? ((pp[0] + pp[1]) + (pp[2] + pp[3])) : (wc < 2 ? pp[0] + pp[1] : pp[2] + pp[3]);
;                         mm = rs * rsqrtf(tot * rs * rs * invW + EPS); }
;                     f32x4 v0 = acc[ai][bj][m][0] * mm * g0, v1 = acc[ai][bj][m][1] * mm * g1;
;                     if (act) {
; #pragma unroll
;                         for (int j = 0; j < 4; ++j) { v0[j] = gelu_tanh_f(v0[j]); v1[j] = gelu_tanh_f(v1[j]); } }
;                     u32x4 w; w.x = cvt_pk_bf16(v0[0], v0[1]); w.y = cvt_pk_bf16(v0[2], v0[3]); w.z = cvt_pk_bf16(v1[0], v1[1]); w.w = cvt_pk_bf16(v1[2], v1[3]);
;                     __builtin_nontemporal_store(w, (u32x4*)(rowp + bj * 128)); } } }
.LBB0_469:
	v_add_u32_e32 v86, 0xa0, v154
	v_mad_i64_i32 v[86:87], s[0:1], v86, s31, 0
	v_lshl_add_u64 v[86:87], v[86:87], 1, v[156:157]
	s_and_b64 vcc, exec, s[6:7]
	v_cvt_pk_bf16_f32 v100, v84, v85
	v_cvt_pk_bf16_f32 v101, v82, v83
	v_cvt_pk_bf16_f32 v102, v98, v99
	v_cvt_pk_bf16_f32 v103, v88, v89
	global_store_dwordx4 v[86:87], v[100:103], off nt
	s_cbranch_vccnz .LBB0_479
	s_add_i32 s0, 0, 0x20000
	v_add_u32_e32 v82, s0, v184
	ds_read_b128 v[82:85], v82 offset:5136
	s_and_b64 vcc, exec, s[10:11]
	s_mov_b64 s[0:1], -1
	s_cbranch_vccnz .LBB0_476
	s_andn2_b64 vcc, exec, s[34:35]
	s_cbranch_vccnz .LBB0_473
	s_waitcnt lgkmcnt(0)
	v_add_f32_e32 v88, v84, v85
	s_mov_b64 s[0:1], 0

; __device__ __forceinline__ unsigned cvt_pk_bf16(float lo, float hi) { unsigned r; asm volatile("v_cvt_pk_bf16_f32 %0, %1, %2" : "=v"(r) : "v"(lo), "v"(hi)); return r; }
; #define LAS __attribute__((address_space(3)))
; __device__ __forceinline__ float gelu_tanh_f(float x) { const float u = 0.7978845608028654f * (x + 0.044715f * x * x * x); return x * fast_rcp(1.f + fast_exp2(-2.f * LOG2E * u)); }
;     __device__ __forceinline__ void operator()(const f32x4 (&acc)[2][2][4][2], const pg8::Unit& u, int wr, int wc, int fr, int fq) const {
;     ...
;             for (int m = 0; m < 4; ++m) { bf16_t* rowp = Z + (size_t)(row0 + ai * 128 + m * 16) * ldc + col0;
;                 const float rs = rsv[m];
; #pragma unroll
;                 for (int bj = 0; bj < 2; ++bj) { float mm = rs;
;                     if (W) { const f32x4 pp = *(const LAS f32x4*)(part + (lrow0 + ai * 128 + m * 16) * 8 + bj * 4);
;                         const float tot = (W == 128) ? ((pp[0] + pp[1]) + (pp[2] + pp[3])) : (wc < 2 ? pp[0] + pp[1] : pp[2] + pp[3]);
;                         mm = rs * rsqrtf(tot * rs * rs * invW + EPS); }
;                     f32x4 v0 = acc[ai][bj][m][0] * mm * g0, v1 = acc[ai][bj][m][1] * mm * g1;
;                     if (act) {
; #pragma unroll
;                         for (int j = 0; j < 4; ++j) { v0[j] = gelu_tanh_f(v0[j]); v1[j] = gelu_tanh_f(v1[j]); } }
;                     u32x4 w; w.x = cvt_pk_bf16(v0[0], v0[1]); w.y = cvt_pk_bf16(v0[2], v0[3]); w.z = cvt_pk_bf16(v1[0], v1[1]); w.w = cvt_pk_bf16(v1[2], v1[3]);
;                     __builtin_nontemporal_store(w, (u32x4*)(rowp + bj * 128)); } } }
.LBB0_481:
	v_cvt_pk_bf16_f32 v80, v80, v81
	v_cvt_pk_bf16_f32 v81, v78, v79
	s_and_b64 vcc, exec, s[6:7]
	v_mov_b32_e32 v78, v0
	v_cvt_pk_bf16_f32 v82, v76, v77
	v_cvt_pk_bf16_f32 v83, v74, v75
	global_store_dwordx4 v[86:87], v[80:83], off offset:256 nt
	s_cbranch_vccnz .LBB0_491
	s_add_i32 s0, 0, 0x20000
	v_add_u32_e32 v74, s0, v184
	ds_read_b128 v[74:77], v74 offset:5632
	s_and_b64 vcc, exec, s[10:11]
	s_mov_b64 s[0:1], -1
	s_cbranch_vccnz .LBB0_488
	s_andn2_b64 vcc, exec, s[34:35]
	s_cbranch_vccnz .LBB0_485
	s_waitcnt lgkmcnt(0)
	v_add_f32_e32 v78, v76, v77
	s_mov_b64 s[0:1], 0

; __device__ __forceinline__ unsigned cvt_pk_bf16(float lo, float hi) { unsigned r; asm volatile("v_cvt_pk_bf16_f32 %0, %1, %2" : "=v"(r) : "v"(lo), "v"(hi)); return r; }
; #define LAS __attribute__((address_space(3)))
; __device__ __forceinline__ float gelu_tanh_f(float x) { const float u = 0.7978845608028654f * (x + 0.044715f * x * x * x); return x * fast_rcp(1.f + fast_exp2(-2.f * LOG2E * u)); }
;     __device__ __forceinline__ void operator()(const f32x4 (&acc)[2][2][4][2], const pg8::Unit& u, int wr, int wc, int fr, int fq) const {
;     ...
;             for (int m = 0; m < 4; ++m) { bf16_t* rowp = Z + (size_t)(row0 + ai * 128 + m * 16) * ldc + col0;
;                 const float rs = rsv[m];
; #pragma unroll
;                 for (int bj = 0; bj < 2; ++bj) { float mm = rs;
;                     if (W) { const f32x4 pp = *(const LAS f32x4*)(part + (lrow0 + ai * 128 + m * 16) * 8 + bj * 4);
;                         const float tot = (W == 128) ? ((pp[0] + pp[1]) + (pp[2] + pp[3])) : (wc < 2 ? pp[0] + pp[1] : pp[2] + pp[3]);
;                         mm = rs * rsqrtf(tot * rs * rs * invW + EPS); }
;                     f32x4 v0 = acc[ai][bj][m][0] * mm * g0, v1 = acc[ai][bj][m][1] * mm * g1;
;                     if (act) {
; #pragma unroll
;                         for (int j = 0; j < 4; ++j) { v0[j] = gelu_tanh_f(v0[j]); v1[j] = gelu_tanh_f(v1[j]); } }
;                     u32x4 w; w.x = cvt_pk_bf16(v0[0], v0[1]); w.y = cvt_pk_bf16(v0[2], v0[3]); w.z = cvt_pk_bf16(v1[0], v1[1]); w.w = cvt_pk_bf16(v1[2], v1[3]);
;                     __builtin_nontemporal_store(w, (u32x4*)(rowp + bj * 128)); } } }
.LBB0_493:
	v_add_u32_e32 v78, 0xb0, v154
	v_mad_i64_i32 v[78:79], s[0:1], v78, s31, 0
	v_lshl_add_u64 v[78:79], v[78:79], 1, v[156:157]
	s_and_b64 vcc, exec, s[6:7]
	v_cvt_pk_bf16_f32 v84, v76, v77
	v_cvt_pk_bf16_f32 v85, v74, v75
	v_cvt_pk_bf16_f32 v86, v82, v83
	v_cvt_pk_bf16_f32 v87, v80, v81
	global_store_dwordx4 v[78:79], v[84:87], off nt
	s_cbranch_vccnz .LBB0_503
	s_add_i32 s0, 0, 0x20000
	v_add_u32_e32 v74, s0, v184
	ds_read_b128 v[74:77], v74 offset:5648
	s_and_b64 vcc, exec, s[10:11]
	s_mov_b64 s[0:1], -1
	s_cbranch_vccnz .LBB0_500
	s_andn2_b64 vcc, exec, s[34:35]
	s_cbranch_vccnz .LBB0_497
	s_waitcnt lgkmcnt(0)
	v_add_f32_e32 v80, v76, v77
	s_mov_b64 s[0:1], 0

; __device__ __forceinline__ unsigned cvt_pk_bf16(float lo, float hi) { unsigned r; asm volatile("v_cvt_pk_bf16_f32 %0, %1, %2" : "=v"(r) : "v"(lo), "v"(hi)); return r; }
; #define LAS __attribute__((address_space(3)))
; __device__ __forceinline__ float gelu_tanh_f(float x) { const float u = 0.7978845608028654f * (x + 0.044715f * x * x * x); return x * fast_rcp(1.f + fast_exp2(-2.f * LOG2E * u)); }
;     __device__ __forceinline__ void operator()(const f32x4 (&acc)[2][2][4][2], const pg8::Unit& u, int wr, int wc, int fr, int fq) const {
;     ...
;             for (int m = 0; m < 4; ++m) { bf16_t* rowp = Z + (size_t)(row0 + ai * 128 + m * 16) * ldc + col0;
;                 const float rs = rsv[m];
; #pragma unroll
;                 for (int bj = 0; bj < 2; ++bj) { float mm = rs;
;                     if (W) { const f32x4 pp = *(const LAS f32x4*)(part + (lrow0 + ai * 128 + m * 16) * 8 + bj * 4);
;                         const float tot = (W == 128) ? ((pp[0] + pp[1]) + (pp[2] + pp[3])) : (wc < 2 ? pp[0] + pp[1] : pp[2] + pp[3]);
;                         mm = rs * rsqrtf(tot * rs * rs * invW + EPS); }
;                     f32x4 v0 = acc[ai][bj][m][0] * mm * g0, v1 = acc[ai][bj][m][1] * mm * g1;
;                     if (act) {
; #pragma unroll
;                         for (int j = 0; j < 4; ++j) { v0[j] = gelu_tanh_f(v0[j]); v1[j] = gelu_tanh_f(v1[j]); } }
;                     u32x4 w; w.x = cvt_pk_bf16(v0[0], v0[1]); w.y = cvt_pk_bf16(v0[2], v0[3]); w.z = cvt_pk_bf16(v1[0], v1[1]); w.w = cvt_pk_bf16(v1[2], v1[3]);
;                     __builtin_nontemporal_store(w, (u32x4*)(rowp + bj * 128)); } } }
.LBB0_505:
	s_mov_b64 s[6:7], 0
	v_cvt_pk_bf16_f32 v72, v72, v73
	v_cvt_pk_bf16_f32 v73, v70, v71
	v_cvt_pk_bf16_f32 v74, v68, v69
	v_cvt_pk_bf16_f32 v75, v66, v67
	global_store_dwordx4 v[78:79], v[72:75], off offset:256 nt
